# conversion output stores marked nt (streaming) to limit cache pollution during slots
# baseline (speedup 1.0000x reference)
.LBB0_20:
	v_lshl_add_u64 v[36:37], v[20:21], 0, s[20:21]
	v_lshl_add_u64 v[38:39], v[18:19], 0, s[20:21]
	v_lshl_add_u64 v[40:41], v[16:17], 0, s[20:21]
	v_lshl_add_u64 v[42:43], v[14:15], 0, s[20:21]
	v_lshl_add_u64 v[44:45], v[12:13], 0, s[20:21]
	v_lshl_add_u64 v[46:47], v[10:11], 0, s[20:21]
	v_lshl_add_u64 v[48:49], v[8:9], 0, s[20:21]
	v_lshl_add_u64 v[50:51], v[6:7], 0, s[20:21]
	global_load_dword v52, v[36:37], off nt
	global_load_dword v53, v[38:39], off nt
	global_load_dword v54, v[40:41], off nt
	global_load_dword v55, v[42:43], off nt
	global_load_dword v56, v[44:45], off nt
	global_load_dword v57, v[46:47], off nt
	global_load_dword v58, v[48:49], off nt
	global_load_dword v59, v[50:51], off nt
	s_add_u32 s20, s20, 0x20000
	s_addc_u32 s21, s21, 0
	v_lshl_add_u64 v[36:37], v[20:21], 0, s[20:21]
	v_lshl_add_u64 v[38:39], v[18:19], 0, s[20:21]
	v_lshl_add_u64 v[40:41], v[16:17], 0, s[20:21]
	v_lshl_add_u64 v[42:43], v[14:15], 0, s[20:21]
	v_lshl_add_u64 v[44:45], v[12:13], 0, s[20:21]
	v_lshl_add_u64 v[46:47], v[10:11], 0, s[20:21]
	v_lshl_add_u64 v[48:49], v[8:9], 0, s[20:21]
	v_lshl_add_u64 v[50:51], v[6:7], 0, s[20:21]
	global_load_dword v60, v[36:37], off nt
	global_load_dword v61, v[38:39], off nt
	global_load_dword v62, v[40:41], off nt
	global_load_dword v63, v[42:43], off nt
	global_load_dword v64, v[44:45], off nt
	global_load_dword v65, v[46:47], off nt
	global_load_dword v66, v[48:49], off nt
	global_load_dword v67, v[50:51], off nt
	s_add_u32 s20, s20, 0x20000
	s_addc_u32 s21, s21, 0
	v_lshl_add_u64 v[36:37], v[20:21], 0, s[20:21]
	v_lshl_add_u64 v[38:39], v[18:19], 0, s[20:21]
	v_lshl_add_u64 v[40:41], v[16:17], 0, s[20:21]
	v_lshl_add_u64 v[42:43], v[14:15], 0, s[20:21]
	v_lshl_add_u64 v[44:45], v[12:13], 0, s[20:21]
	v_lshl_add_u64 v[46:47], v[10:11], 0, s[20:21]
	v_lshl_add_u64 v[48:49], v[8:9], 0, s[20:21]
	v_lshl_add_u64 v[50:51], v[6:7], 0, s[20:21]
	global_load_dword v68, v[36:37], off nt
	global_load_dword v69, v[38:39], off nt
	global_load_dword v70, v[40:41], off nt
	global_load_dword v71, v[42:43], off nt
	global_load_dword v72, v[44:45], off nt
	global_load_dword v73, v[46:47], off nt
	global_load_dword v74, v[48:49], off nt
	global_load_dword v75, v[50:51], off nt
	s_add_u32 s20, s20, 0x20000
	s_addc_u32 s21, s21, 0
	v_lshl_add_u64 v[36:37], v[20:21], 0, s[20:21]
	v_lshl_add_u64 v[38:39], v[18:19], 0, s[20:21]
	v_lshl_add_u64 v[40:41], v[16:17], 0, s[20:21]
	v_lshl_add_u64 v[42:43], v[14:15], 0, s[20:21]
	v_lshl_add_u64 v[44:45], v[12:13], 0, s[20:21]
	v_lshl_add_u64 v[46:47], v[10:11], 0, s[20:21]
	v_lshl_add_u64 v[48:49], v[8:9], 0, s[20:21]
	v_lshl_add_u64 v[50:51], v[6:7], 0, s[20:21]
	global_load_dword v76, v[36:37], off nt
	global_load_dword v77, v[38:39], off nt
	global_load_dword v78, v[40:41], off nt
	global_load_dword v79, v[42:43], off nt
	global_load_dword v80, v[44:45], off nt
	global_load_dword v81, v[46:47], off nt
	global_load_dword v82, v[48:49], off nt
	global_load_dword v83, v[50:51], off nt
	s_add_u32 s20, s20, 0x20000
	s_addc_u32 s21, s21, 0
	v_add_u32_e32 v36, 0x400, v35
	s_waitcnt vmcnt(30)
	ds_write2_b32 v35, v52, v53 offset1:66
	s_waitcnt vmcnt(28)
	ds_write2_b32 v35, v54, v55 offset0:132 offset1:198
	s_waitcnt vmcnt(26)
	ds_write2_b32 v36, v56, v57 offset0:8 offset1:74
	s_waitcnt vmcnt(24)
	ds_write2_b32 v36, v58, v59 offset0:140 offset1:206
	v_add_u32_e32 v35, 0x840, v35
	v_add_u32_e32 v36, 0x400, v35
	s_waitcnt vmcnt(22)
	ds_write2_b32 v35, v60, v61 offset1:66
	s_waitcnt vmcnt(20)
	ds_write2_b32 v35, v62, v63 offset0:132 offset1:198
	s_waitcnt vmcnt(18)
	ds_write2_b32 v36, v64, v65 offset0:8 offset1:74
	s_waitcnt vmcnt(16)
	ds_write2_b32 v36, v66, v67 offset0:140 offset1:206
	v_add_u32_e32 v35, 0x840, v35
	v_add_u32_e32 v36, 0x400, v35
	s_waitcnt vmcnt(14)
	ds_write2_b32 v35, v68, v69 offset1:66
	s_waitcnt vmcnt(12)
	ds_write2_b32 v35, v70, v71 offset0:132 offset1:198
	s_waitcnt vmcnt(10)
	ds_write2_b32 v36, v72, v73 offset0:8 offset1:74
	s_waitcnt vmcnt(8)
	ds_write2_b32 v36, v74, v75 offset0:140 offset1:206
	v_add_u32_e32 v35, 0x840, v35
	v_add_u32_e32 v36, 0x400, v35
	s_waitcnt vmcnt(6)
	ds_write2_b32 v35, v76, v77 offset1:66
	s_waitcnt vmcnt(4)
	ds_write2_b32 v35, v78, v79 offset0:132 offset1:198
	s_waitcnt vmcnt(2)
	ds_write2_b32 v36, v80, v81 offset0:8 offset1:74
	s_waitcnt vmcnt(0)
	ds_write2_b32 v36, v82, v83 offset0:140 offset1:206
	v_add_u32_e32 v35, 0x840, v35
	s_waitcnt lgkmcnt(0)
	s_lshl_b32 s20, s22, 5
	ds_read2_b32 v[10:11], v23 offset1:8
	s_and_b32 s33, s20, 0x7e0
	s_lshl_b32 s20, s23, 1
	ds_read2_b32 v[14:15], v23 offset0:33 offset1:41
	s_add_u32 s20, s30, s20
	s_addc_u32 s21, s31, 0
	ds_read2_b32 v[16:17], v23 offset0:66 offset1:74
	v_lshl_add_u64 v[6:7], s[20:21], 0, v[2:3]
	ds_read2_b32 v[18:19], v23 offset0:99 offset1:107
	v_lshl_add_u64 v[12:13], v[6:7], 0, s[4:5]
	s_waitcnt lgkmcnt(3)
	v_bfe_u32 v6, v10, 16, 1
	v_add3_u32 v6, v10, v6, s26
	s_waitcnt lgkmcnt(2)
	v_bfe_u32 v7, v14, 16, 1
	ds_read2_b32 v[20:21], v23 offset0:132 offset1:140
	v_lshrrev_b32_e32 v6, 16, v6
	v_add3_u32 v7, v14, v7, s26
	ds_read2_b32 v[36:37], v23 offset0:165 offset1:173
	v_and_or_b32 v6, v7, s27, v6
	s_waitcnt lgkmcnt(3)
	v_bfe_u32 v7, v16, 16, 1
	v_add3_u32 v7, v16, v7, s26
	s_waitcnt lgkmcnt(2)
	v_bfe_u32 v8, v18, 16, 1
	ds_read2_b32 v[38:39], v23 offset0:198 offset1:206
	v_lshrrev_b32_e32 v7, 16, v7
	v_add3_u32 v8, v18, v8, s26
	ds_read2_b32 v[40:41], v23 offset0:231 offset1:239
	v_and_or_b32 v7, v8, s27, v7
	s_waitcnt lgkmcnt(3)
	v_bfe_u32 v8, v20, 16, 1
	v_add3_u32 v8, v20, v8, s26
	s_waitcnt lgkmcnt(2)
	v_bfe_u32 v9, v36, 16, 1
	v_lshrrev_b32_e32 v8, 16, v8
	v_add3_u32 v9, v36, v9, s26
	v_and_or_b32 v8, v9, s27, v8
	s_waitcnt lgkmcnt(1)
	v_bfe_u32 v9, v38, 16, 1
	v_add3_u32 v9, v38, v9, s26
	s_waitcnt lgkmcnt(0)
	v_bfe_u32 v10, v40, 16, 1
	v_lshrrev_b32_e32 v9, 16, v9
	v_add3_u32 v10, v40, v10, s26
	v_and_or_b32 v9, v10, s27, v9
	v_or_b32_e32 v10, s33, v22
	v_mul_u32_u24_e32 v10, 0x1600, v10
	v_lshlrev_b32_e32 v42, 1, v10
	v_mov_b32_e32 v43, v3
	v_lshl_add_u64 v[42:43], v[12:13], 0, v[42:43]
	global_store_dwordx4 v[42:43], v[6:9], off nt
	v_bfe_u32 v10, v41, 16, 1
	v_add3_u32 v10, v41, v10, s26
	v_bfe_u32 v6, v11, 16, 1
	v_add3_u32 v6, v11, v6, s26
	v_bfe_u32 v7, v15, 16, 1
	v_lshrrev_b32_e32 v6, 16, v6
	v_add3_u32 v7, v15, v7, s26
	v_and_or_b32 v6, v7, s27, v6
	v_bfe_u32 v7, v17, 16, 1
	v_add3_u32 v7, v17, v7, s26
	v_bfe_u32 v8, v19, 16, 1
	v_lshrrev_b32_e32 v7, 16, v7
	v_add3_u32 v8, v19, v8, s26
	v_and_or_b32 v7, v8, s27, v7
	v_bfe_u32 v8, v21, 16, 1
	v_add3_u32 v8, v21, v8, s26
	v_bfe_u32 v9, v37, 16, 1
	v_lshrrev_b32_e32 v8, 16, v8
	v_add3_u32 v9, v37, v9, s26
	v_and_or_b32 v8, v9, s27, v8
	v_bfe_u32 v9, v39, 16, 1
	v_add3_u32 v9, v39, v9, s26
	v_lshrrev_b32_e32 v9, 16, v9
	v_and_or_b32 v9, v10, s27, v9
	v_or_b32_e32 v10, s33, v24
	v_mul_u32_u24_e32 v10, 0x1600, v10
	v_lshlrev_b32_e32 v10, 1, v10
	v_mov_b32_e32 v11, v3
	ds_read2_b32 v[14:15], v23 offset0:16 offset1:24
	v_lshl_add_u64 v[10:11], v[12:13], 0, v[10:11]
	global_store_dwordx4 v[10:11], v[6:9], off nt
	ds_read2_b32 v[10:11], v23 offset0:49 offset1:57
	ds_read2_b32 v[16:17], v23 offset0:82 offset1:90
	ds_read2_b32 v[18:19], v23 offset0:115 offset1:123
	s_waitcnt lgkmcnt(3)
	v_bfe_u32 v6, v14, 16, 1
	v_add3_u32 v6, v14, v6, s26
	s_waitcnt lgkmcnt(2)
	v_bfe_u32 v7, v10, 16, 1
	ds_read2_b32 v[20:21], v23 offset0:148 offset1:156
	v_lshrrev_b32_e32 v6, 16, v6
	v_add3_u32 v7, v10, v7, s26
	ds_read2_b32 v[36:37], v23 offset0:181 offset1:189
	v_and_or_b32 v6, v7, s27, v6
	s_waitcnt lgkmcnt(3)
	v_bfe_u32 v7, v16, 16, 1
	v_add3_u32 v7, v16, v7, s26
	s_waitcnt lgkmcnt(2)
	v_bfe_u32 v8, v18, 16, 1
	ds_read2_b32 v[38:39], v23 offset0:214 offset1:222
	v_lshrrev_b32_e32 v7, 16, v7
	v_add3_u32 v8, v18, v8, s26
	ds_read2_b32 v[40:41], v23 offset0:247 offset1:255
	v_and_or_b32 v7, v8, s27, v7
	s_waitcnt lgkmcnt(3)
	v_bfe_u32 v8, v20, 16, 1
	v_add3_u32 v8, v20, v8, s26
	s_waitcnt lgkmcnt(2)
	v_bfe_u32 v9, v36, 16, 1
	v_lshrrev_b32_e32 v8, 16, v8
	v_add3_u32 v9, v36, v9, s26
	v_and_or_b32 v8, v9, s27, v8
	s_waitcnt lgkmcnt(1)
	v_bfe_u32 v9, v38, 16, 1
	v_add3_u32 v9, v38, v9, s26
	s_waitcnt lgkmcnt(0)
	v_bfe_u32 v10, v40, 16, 1
	v_lshrrev_b32_e32 v9, 16, v9
	v_add3_u32 v10, v40, v10, s26
	v_and_or_b32 v9, v10, s27, v9
	v_or_b32_e32 v10, s33, v25
	v_mul_u32_u24_e32 v10, 0x1600, v10
	v_lshlrev_b32_e32 v42, 1, v10
	v_mov_b32_e32 v43, v3
	v_lshl_add_u64 v[42:43], v[12:13], 0, v[42:43]
	global_store_dwordx4 v[42:43], v[6:9], off nt
	v_bfe_u32 v10, v41, 16, 1
	v_add3_u32 v10, v41, v10, s26
	v_bfe_u32 v6, v15, 16, 1
	v_add3_u32 v6, v15, v6, s26
	v_bfe_u32 v7, v11, 16, 1
	v_lshrrev_b32_e32 v6, 16, v6
	v_add3_u32 v7, v11, v7, s26
	v_and_or_b32 v6, v7, s27, v6
	v_bfe_u32 v7, v17, 16, 1
	v_add3_u32 v7, v17, v7, s26
	v_bfe_u32 v8, v19, 16, 1
	v_lshrrev_b32_e32 v7, 16, v7
	v_add3_u32 v8, v19, v8, s26
	v_and_or_b32 v7, v8, s27, v7
	v_bfe_u32 v8, v21, 16, 1
	v_add3_u32 v8, v21, v8, s26
	v_bfe_u32 v9, v37, 16, 1
	v_lshrrev_b32_e32 v8, 16, v8
	v_add3_u32 v9, v37, v9, s26
	v_and_or_b32 v8, v9, s27, v8
	v_bfe_u32 v9, v39, 16, 1
	v_add3_u32 v9, v39, v9, s26
	v_lshrrev_b32_e32 v9, 16, v9
	v_and_or_b32 v9, v10, s27, v9
	v_or_b32_e32 v10, s33, v26
	v_mul_u32_u24_e32 v10, 0x1600, v10
	v_lshlrev_b32_e32 v10, 1, v10
	v_mov_b32_e32 v11, v3
	v_lshl_add_u64 v[10:11], v[12:13], 0, v[10:11]
	global_store_dwordx4 v[10:11], v[6:9], off nt
	s_waitcnt lgkmcnt(0)
	s_mov_b64 s[20:21], 0

.LBB0_24:
	v_lshl_add_u64 v[36:37], v[20:21], 0, s[20:21]
	v_lshl_add_u64 v[38:39], v[18:19], 0, s[20:21]
	v_lshl_add_u64 v[40:41], v[16:17], 0, s[20:21]
	v_lshl_add_u64 v[42:43], v[14:15], 0, s[20:21]
	v_lshl_add_u64 v[44:45], v[12:13], 0, s[20:21]
	v_lshl_add_u64 v[46:47], v[10:11], 0, s[20:21]
	v_lshl_add_u64 v[48:49], v[8:9], 0, s[20:21]
	v_lshl_add_u64 v[50:51], v[6:7], 0, s[20:21]
	global_load_dword v52, v[36:37], off nt
	global_load_dword v53, v[38:39], off nt
	global_load_dword v54, v[40:41], off nt
	global_load_dword v55, v[42:43], off nt
	global_load_dword v56, v[44:45], off nt
	global_load_dword v57, v[46:47], off nt
	global_load_dword v58, v[48:49], off nt
	global_load_dword v59, v[50:51], off nt
	s_add_u32 s20, s20, 0x58000
	s_addc_u32 s21, s21, 0
	v_lshl_add_u64 v[36:37], v[20:21], 0, s[20:21]
	v_lshl_add_u64 v[38:39], v[18:19], 0, s[20:21]
	v_lshl_add_u64 v[40:41], v[16:17], 0, s[20:21]
	v_lshl_add_u64 v[42:43], v[14:15], 0, s[20:21]
	v_lshl_add_u64 v[44:45], v[12:13], 0, s[20:21]
	v_lshl_add_u64 v[46:47], v[10:11], 0, s[20:21]
	v_lshl_add_u64 v[48:49], v[8:9], 0, s[20:21]
	v_lshl_add_u64 v[50:51], v[6:7], 0, s[20:21]
	global_load_dword v60, v[36:37], off nt
	global_load_dword v61, v[38:39], off nt
	global_load_dword v62, v[40:41], off nt
	global_load_dword v63, v[42:43], off nt
	global_load_dword v64, v[44:45], off nt
	global_load_dword v65, v[46:47], off nt
	global_load_dword v66, v[48:49], off nt
	global_load_dword v67, v[50:51], off nt
	s_add_u32 s20, s20, 0x58000
	s_addc_u32 s21, s21, 0
	v_lshl_add_u64 v[36:37], v[20:21], 0, s[20:21]
	v_lshl_add_u64 v[38:39], v[18:19], 0, s[20:21]
	v_lshl_add_u64 v[40:41], v[16:17], 0, s[20:21]
	v_lshl_add_u64 v[42:43], v[14:15], 0, s[20:21]
	v_lshl_add_u64 v[44:45], v[12:13], 0, s[20:21]
	v_lshl_add_u64 v[46:47], v[10:11], 0, s[20:21]
	v_lshl_add_u64 v[48:49], v[8:9], 0, s[20:21]
	v_lshl_add_u64 v[50:51], v[6:7], 0, s[20:21]
	global_load_dword v68, v[36:37], off nt
	global_load_dword v69, v[38:39], off nt
	global_load_dword v70, v[40:41], off nt
	global_load_dword v71, v[42:43], off nt
	global_load_dword v72, v[44:45], off nt
	global_load_dword v73, v[46:47], off nt
	global_load_dword v74, v[48:49], off nt
	global_load_dword v75, v[50:51], off nt
	s_add_u32 s20, s20, 0x58000
	s_addc_u32 s21, s21, 0
	v_lshl_add_u64 v[36:37], v[20:21], 0, s[20:21]
	v_lshl_add_u64 v[38:39], v[18:19], 0, s[20:21]
	v_lshl_add_u64 v[40:41], v[16:17], 0, s[20:21]
	v_lshl_add_u64 v[42:43], v[14:15], 0, s[20:21]
	v_lshl_add_u64 v[44:45], v[12:13], 0, s[20:21]
	v_lshl_add_u64 v[46:47], v[10:11], 0, s[20:21]
	v_lshl_add_u64 v[48:49], v[8:9], 0, s[20:21]
	v_lshl_add_u64 v[50:51], v[6:7], 0, s[20:21]
	global_load_dword v76, v[36:37], off nt
	global_load_dword v77, v[38:39], off nt
	global_load_dword v78, v[40:41], off nt
	global_load_dword v79, v[42:43], off nt
	global_load_dword v80, v[44:45], off nt
	global_load_dword v81, v[46:47], off nt
	global_load_dword v82, v[48:49], off nt
	global_load_dword v83, v[50:51], off nt
	s_add_u32 s20, s20, 0x58000
	s_addc_u32 s21, s21, 0
	v_add_u32_e32 v36, 0x400, v35
	s_waitcnt vmcnt(30)
	ds_write2_b32 v35, v52, v53 offset1:66
	s_waitcnt vmcnt(28)
	ds_write2_b32 v35, v54, v55 offset0:132 offset1:198
	s_waitcnt vmcnt(26)
	ds_write2_b32 v36, v56, v57 offset0:8 offset1:74
	s_waitcnt vmcnt(24)
	ds_write2_b32 v36, v58, v59 offset0:140 offset1:206
	v_add_u32_e32 v35, 0x840, v35
	v_add_u32_e32 v36, 0x400, v35
	s_waitcnt vmcnt(22)
	ds_write2_b32 v35, v60, v61 offset1:66
	s_waitcnt vmcnt(20)
	ds_write2_b32 v35, v62, v63 offset0:132 offset1:198
	s_waitcnt vmcnt(18)
	ds_write2_b32 v36, v64, v65 offset0:8 offset1:74
	s_waitcnt vmcnt(16)
	ds_write2_b32 v36, v66, v67 offset0:140 offset1:206
	v_add_u32_e32 v35, 0x840, v35
	v_add_u32_e32 v36, 0x400, v35
	s_waitcnt vmcnt(14)
	ds_write2_b32 v35, v68, v69 offset1:66
	s_waitcnt vmcnt(12)
	ds_write2_b32 v35, v70, v71 offset0:132 offset1:198
	s_waitcnt vmcnt(10)
	ds_write2_b32 v36, v72, v73 offset0:8 offset1:74
	s_waitcnt vmcnt(8)
	ds_write2_b32 v36, v74, v75 offset0:140 offset1:206
	v_add_u32_e32 v35, 0x840, v35
	v_add_u32_e32 v36, 0x400, v35
	s_waitcnt vmcnt(6)
	ds_write2_b32 v35, v76, v77 offset1:66
	s_waitcnt vmcnt(4)
	ds_write2_b32 v35, v78, v79 offset0:132 offset1:198
	s_waitcnt vmcnt(2)
	ds_write2_b32 v36, v80, v81 offset0:8 offset1:74
	s_waitcnt vmcnt(0)
	ds_write2_b32 v36, v82, v83 offset0:140 offset1:206
	v_add_u32_e32 v35, 0x840, v35
	s_lshl_b32 s20, s33, 5
	s_lshl_b32 s21, s33, 6
	s_and_b32 s21, s21, 0x3f00
	s_and_b32 s20, s20, 0x60
	s_waitcnt lgkmcnt(0)
	s_or_b32 s20, s21, s20
	s_or_b32 s33, s20, 0x80
	s_and_b32 s20, 0xffff, s23
	ds_read2_b32 v[10:11], v23 offset1:8
	s_lshl_b32 s20, s20, 1
	ds_read2_b32 v[14:15], v23 offset0:33 offset1:41
	s_add_u32 s20, s30, s20
	s_addc_u32 s21, s31, 0
	ds_read2_b32 v[16:17], v23 offset0:66 offset1:74
	v_lshl_add_u64 v[6:7], s[20:21], 0, v[2:3]
	ds_read2_b32 v[18:19], v23 offset0:99 offset1:107
	v_lshl_add_u64 v[12:13], v[6:7], 0, s[6:7]
	s_waitcnt lgkmcnt(3)
	v_bfe_u32 v6, v10, 16, 1
	v_add3_u32 v6, v10, v6, s26
	s_waitcnt lgkmcnt(2)
	v_bfe_u32 v7, v14, 16, 1
	ds_read2_b32 v[20:21], v23 offset0:132 offset1:140
	v_lshrrev_b32_e32 v6, 16, v6
	v_add3_u32 v7, v14, v7, s26
	ds_read2_b32 v[36:37], v23 offset0:165 offset1:173
	v_and_or_b32 v6, v7, s27, v6
	s_waitcnt lgkmcnt(3)
	v_bfe_u32 v7, v16, 16, 1
	v_add3_u32 v7, v16, v7, s26
	s_waitcnt lgkmcnt(2)
	v_bfe_u32 v8, v18, 16, 1
	ds_read2_b32 v[38:39], v23 offset0:198 offset1:206
	v_lshrrev_b32_e32 v7, 16, v7
	v_add3_u32 v8, v18, v8, s26
	ds_read2_b32 v[40:41], v23 offset0:231 offset1:239
	v_and_or_b32 v7, v8, s27, v7
	s_waitcnt lgkmcnt(3)
	v_bfe_u32 v8, v20, 16, 1
	v_add3_u32 v8, v20, v8, s26
	s_waitcnt lgkmcnt(2)
	v_bfe_u32 v9, v36, 16, 1
	v_lshrrev_b32_e32 v8, 16, v8
	v_add3_u32 v9, v36, v9, s26
	v_and_or_b32 v8, v9, s27, v8
	s_waitcnt lgkmcnt(1)
	v_bfe_u32 v9, v38, 16, 1
	v_add3_u32 v9, v38, v9, s26
	s_waitcnt lgkmcnt(0)
	v_bfe_u32 v10, v40, 16, 1
	v_lshrrev_b32_e32 v9, 16, v9
	v_add3_u32 v10, v40, v10, s26
	v_and_or_b32 v9, v10, s27, v9
	v_or_b32_e32 v10, s33, v22
	v_lshlrev_b32_e32 v42, 12, v10
	v_mov_b32_e32 v43, v3
	v_lshl_add_u64 v[42:43], v[12:13], 0, v[42:43]
	global_store_dwordx4 v[42:43], v[6:9], off nt
	v_bfe_u32 v10, v41, 16, 1
	v_add3_u32 v10, v41, v10, s26
	v_bfe_u32 v6, v11, 16, 1
	v_add3_u32 v6, v11, v6, s26
	v_bfe_u32 v7, v15, 16, 1
	v_lshrrev_b32_e32 v6, 16, v6
	v_add3_u32 v7, v15, v7, s26
	v_and_or_b32 v6, v7, s27, v6
	v_bfe_u32 v7, v17, 16, 1
	v_add3_u32 v7, v17, v7, s26
	v_bfe_u32 v8, v19, 16, 1
	v_lshrrev_b32_e32 v7, 16, v7
	v_add3_u32 v8, v19, v8, s26
	v_and_or_b32 v7, v8, s27, v7
	v_bfe_u32 v8, v21, 16, 1
	v_add3_u32 v8, v21, v8, s26
	v_bfe_u32 v9, v37, 16, 1
	v_lshrrev_b32_e32 v8, 16, v8
	v_add3_u32 v9, v37, v9, s26
	v_and_or_b32 v8, v9, s27, v8
	v_bfe_u32 v9, v39, 16, 1
	v_add3_u32 v9, v39, v9, s26
	v_lshrrev_b32_e32 v9, 16, v9
	v_and_or_b32 v9, v10, s27, v9
	v_or_b32_e32 v10, s33, v24
	v_lshlrev_b32_e32 v10, 12, v10
	v_mov_b32_e32 v11, v3
	ds_read2_b32 v[14:15], v23 offset0:16 offset1:24
	v_lshl_add_u64 v[10:11], v[12:13], 0, v[10:11]
	global_store_dwordx4 v[10:11], v[6:9], off nt
	ds_read2_b32 v[10:11], v23 offset0:49 offset1:57
	ds_read2_b32 v[16:17], v23 offset0:82 offset1:90
	ds_read2_b32 v[18:19], v23 offset0:115 offset1:123
	s_waitcnt lgkmcnt(3)
	v_bfe_u32 v6, v14, 16, 1
	v_add3_u32 v6, v14, v6, s26
	s_waitcnt lgkmcnt(2)
	v_bfe_u32 v7, v10, 16, 1
	ds_read2_b32 v[20:21], v23 offset0:148 offset1:156
	v_lshrrev_b32_e32 v6, 16, v6
	v_add3_u32 v7, v10, v7, s26
	ds_read2_b32 v[36:37], v23 offset0:181 offset1:189
	v_and_or_b32 v6, v7, s27, v6
	s_waitcnt lgkmcnt(3)
	v_bfe_u32 v7, v16, 16, 1
	v_add3_u32 v7, v16, v7, s26
	s_waitcnt lgkmcnt(2)
	v_bfe_u32 v8, v18, 16, 1
	ds_read2_b32 v[38:39], v23 offset0:214 offset1:222
	v_lshrrev_b32_e32 v7, 16, v7
	v_add3_u32 v8, v18, v8, s26
	ds_read2_b32 v[40:41], v23 offset0:247 offset1:255
	v_and_or_b32 v7, v8, s27, v7
	s_waitcnt lgkmcnt(3)
	v_bfe_u32 v8, v20, 16, 1
	v_add3_u32 v8, v20, v8, s26
	s_waitcnt lgkmcnt(2)
	v_bfe_u32 v9, v36, 16, 1
	v_lshrrev_b32_e32 v8, 16, v8
	v_add3_u32 v9, v36, v9, s26
	v_and_or_b32 v8, v9, s27, v8
	s_waitcnt lgkmcnt(1)
	v_bfe_u32 v9, v38, 16, 1
	v_add3_u32 v9, v38, v9, s26
	s_waitcnt lgkmcnt(0)
	v_bfe_u32 v10, v40, 16, 1
	v_lshrrev_b32_e32 v9, 16, v9
	v_add3_u32 v10, v40, v10, s26
	v_and_or_b32 v9, v10, s27, v9
	v_or_b32_e32 v10, s33, v25
	v_lshlrev_b32_e32 v42, 12, v10
	v_mov_b32_e32 v43, v3
	v_lshl_add_u64 v[42:43], v[12:13], 0, v[42:43]
	global_store_dwordx4 v[42:43], v[6:9], off nt
	v_bfe_u32 v10, v41, 16, 1
	v_add3_u32 v10, v41, v10, s26
	v_bfe_u32 v6, v15, 16, 1
	v_add3_u32 v6, v15, v6, s26
	v_bfe_u32 v7, v11, 16, 1
	v_lshrrev_b32_e32 v6, 16, v6
	v_add3_u32 v7, v11, v7, s26
	v_and_or_b32 v6, v7, s27, v6
	v_bfe_u32 v7, v17, 16, 1
	v_add3_u32 v7, v17, v7, s26
	v_bfe_u32 v8, v19, 16, 1
	v_lshrrev_b32_e32 v7, 16, v7
	v_add3_u32 v8, v19, v8, s26
	v_and_or_b32 v7, v8, s27, v7
	v_bfe_u32 v8, v21, 16, 1
	v_add3_u32 v8, v21, v8, s26
	v_bfe_u32 v9, v37, 16, 1
	v_lshrrev_b32_e32 v8, 16, v8
	v_add3_u32 v9, v37, v9, s26
	v_and_or_b32 v8, v9, s27, v8
	v_bfe_u32 v9, v39, 16, 1
	v_add3_u32 v9, v39, v9, s26
	v_lshrrev_b32_e32 v9, 16, v9
	v_and_or_b32 v9, v10, s27, v9
	v_or_b32_e32 v10, s33, v26
	v_lshlrev_b32_e32 v10, 12, v10
	v_mov_b32_e32 v11, v3
	v_lshl_add_u64 v[10:11], v[12:13], 0, v[10:11]
	global_store_dwordx4 v[10:11], v[6:9], off nt
	s_waitcnt lgkmcnt(0)

.LBB0_29:
	v_lshl_add_u64 v[36:37], v[20:21], 0, s[20:21]
	v_lshl_add_u64 v[38:39], v[18:19], 0, s[20:21]
	v_lshl_add_u64 v[40:41], v[16:17], 0, s[20:21]
	v_lshl_add_u64 v[42:43], v[14:15], 0, s[20:21]
	v_lshl_add_u64 v[44:45], v[12:13], 0, s[20:21]
	v_lshl_add_u64 v[46:47], v[10:11], 0, s[20:21]
	v_lshl_add_u64 v[48:49], v[8:9], 0, s[20:21]
	v_lshl_add_u64 v[50:51], v[6:7], 0, s[20:21]
	global_load_dword v52, v[36:37], off nt
	global_load_dword v53, v[38:39], off nt
	global_load_dword v54, v[40:41], off nt
	global_load_dword v55, v[42:43], off nt
	global_load_dword v56, v[44:45], off nt
	global_load_dword v57, v[46:47], off nt
	global_load_dword v58, v[48:49], off nt
	global_load_dword v59, v[50:51], off nt
	s_add_u32 s20, s20, 0x58000
	s_addc_u32 s21, s21, 0
	v_lshl_add_u64 v[36:37], v[20:21], 0, s[20:21]
	v_lshl_add_u64 v[38:39], v[18:19], 0, s[20:21]
	v_lshl_add_u64 v[40:41], v[16:17], 0, s[20:21]
	v_lshl_add_u64 v[42:43], v[14:15], 0, s[20:21]
	v_lshl_add_u64 v[44:45], v[12:13], 0, s[20:21]
	v_lshl_add_u64 v[46:47], v[10:11], 0, s[20:21]
	v_lshl_add_u64 v[48:49], v[8:9], 0, s[20:21]
	v_lshl_add_u64 v[50:51], v[6:7], 0, s[20:21]
	global_load_dword v60, v[36:37], off nt
	global_load_dword v61, v[38:39], off nt
	global_load_dword v62, v[40:41], off nt
	global_load_dword v63, v[42:43], off nt
	global_load_dword v64, v[44:45], off nt
	global_load_dword v65, v[46:47], off nt
	global_load_dword v66, v[48:49], off nt
	global_load_dword v67, v[50:51], off nt
	s_add_u32 s20, s20, 0x58000
	s_addc_u32 s21, s21, 0
	v_lshl_add_u64 v[36:37], v[20:21], 0, s[20:21]
	v_lshl_add_u64 v[38:39], v[18:19], 0, s[20:21]
	v_lshl_add_u64 v[40:41], v[16:17], 0, s[20:21]
	v_lshl_add_u64 v[42:43], v[14:15], 0, s[20:21]
	v_lshl_add_u64 v[44:45], v[12:13], 0, s[20:21]
	v_lshl_add_u64 v[46:47], v[10:11], 0, s[20:21]
	v_lshl_add_u64 v[48:49], v[8:9], 0, s[20:21]
	v_lshl_add_u64 v[50:51], v[6:7], 0, s[20:21]
	global_load_dword v68, v[36:37], off nt
	global_load_dword v69, v[38:39], off nt
	global_load_dword v70, v[40:41], off nt
	global_load_dword v71, v[42:43], off nt
	global_load_dword v72, v[44:45], off nt
	global_load_dword v73, v[46:47], off nt
	global_load_dword v74, v[48:49], off nt
	global_load_dword v75, v[50:51], off nt
	s_add_u32 s20, s20, 0x58000
	s_addc_u32 s21, s21, 0
	v_lshl_add_u64 v[36:37], v[20:21], 0, s[20:21]
	v_lshl_add_u64 v[38:39], v[18:19], 0, s[20:21]
	v_lshl_add_u64 v[40:41], v[16:17], 0, s[20:21]
	v_lshl_add_u64 v[42:43], v[14:15], 0, s[20:21]
	v_lshl_add_u64 v[44:45], v[12:13], 0, s[20:21]
	v_lshl_add_u64 v[46:47], v[10:11], 0, s[20:21]
	v_lshl_add_u64 v[48:49], v[8:9], 0, s[20:21]
	v_lshl_add_u64 v[50:51], v[6:7], 0, s[20:21]
	global_load_dword v76, v[36:37], off nt
	global_load_dword v77, v[38:39], off nt
	global_load_dword v78, v[40:41], off nt
	global_load_dword v79, v[42:43], off nt
	global_load_dword v80, v[44:45], off nt
	global_load_dword v81, v[46:47], off nt
	global_load_dword v82, v[48:49], off nt
	global_load_dword v83, v[50:51], off nt
	s_add_u32 s20, s20, 0x58000
	s_addc_u32 s21, s21, 0
	v_add_u32_e32 v36, 0x400, v35
	s_waitcnt vmcnt(30)
	ds_write2_b32 v35, v52, v53 offset1:66
	s_waitcnt vmcnt(28)
	ds_write2_b32 v35, v54, v55 offset0:132 offset1:198
	s_waitcnt vmcnt(26)
	ds_write2_b32 v36, v56, v57 offset0:8 offset1:74
	s_waitcnt vmcnt(24)
	ds_write2_b32 v36, v58, v59 offset0:140 offset1:206
	v_add_u32_e32 v35, 0x840, v35
	v_add_u32_e32 v36, 0x400, v35
	s_waitcnt vmcnt(22)
	ds_write2_b32 v35, v60, v61 offset1:66
	s_waitcnt vmcnt(20)
	ds_write2_b32 v35, v62, v63 offset0:132 offset1:198
	s_waitcnt vmcnt(18)
	ds_write2_b32 v36, v64, v65 offset0:8 offset1:74
	s_waitcnt vmcnt(16)
	ds_write2_b32 v36, v66, v67 offset0:140 offset1:206
	v_add_u32_e32 v35, 0x840, v35
	v_add_u32_e32 v36, 0x400, v35
	s_waitcnt vmcnt(14)
	ds_write2_b32 v35, v68, v69 offset1:66
	s_waitcnt vmcnt(12)
	ds_write2_b32 v35, v70, v71 offset0:132 offset1:198
	s_waitcnt vmcnt(10)
	ds_write2_b32 v36, v72, v73 offset0:8 offset1:74
	s_waitcnt vmcnt(8)
	ds_write2_b32 v36, v74, v75 offset0:140 offset1:206
	v_add_u32_e32 v35, 0x840, v35
	v_add_u32_e32 v36, 0x400, v35
	s_waitcnt vmcnt(6)
	ds_write2_b32 v35, v76, v77 offset1:66
	s_waitcnt vmcnt(4)
	ds_write2_b32 v35, v78, v79 offset0:132 offset1:198
	s_waitcnt vmcnt(2)
	ds_write2_b32 v36, v80, v81 offset0:8 offset1:74
	s_waitcnt vmcnt(0)
	ds_write2_b32 v36, v82, v83 offset0:140 offset1:206
	v_add_u32_e32 v35, 0x840, v35
	s_lshl_b32 s20, s33, 5
	s_lshl_b32 s21, s33, 6
	s_waitcnt lgkmcnt(0)
	s_and_b32 s21, s21, 0x3f00
	s_and_b32 s20, s20, 0x60
	s_or_b32 s33, s20, s21
	s_and_b32 s20, 0xffff, s23
	ds_read2_b32 v[10:11], v23 offset1:8
	s_lshl_b32 s20, s20, 1
	ds_read2_b32 v[14:15], v23 offset0:33 offset1:41
	s_add_u32 s20, s30, s20
	s_addc_u32 s21, s31, 0
	ds_read2_b32 v[16:17], v23 offset0:66 offset1:74
	v_lshl_add_u64 v[6:7], s[20:21], 0, v[2:3]
	ds_read2_b32 v[18:19], v23 offset0:99 offset1:107
	v_lshl_add_u64 v[12:13], v[6:7], 0, s[6:7]
	s_waitcnt lgkmcnt(3)
	v_bfe_u32 v6, v10, 16, 1
	v_add3_u32 v6, v10, v6, s26
	s_waitcnt lgkmcnt(2)
	v_bfe_u32 v7, v14, 16, 1
	ds_read2_b32 v[20:21], v23 offset0:132 offset1:140
	v_lshrrev_b32_e32 v6, 16, v6
	v_add3_u32 v7, v14, v7, s26
	ds_read2_b32 v[36:37], v23 offset0:165 offset1:173
	v_and_or_b32 v6, v7, s27, v6
	s_waitcnt lgkmcnt(3)
	v_bfe_u32 v7, v16, 16, 1
	v_add3_u32 v7, v16, v7, s26
	s_waitcnt lgkmcnt(2)
	v_bfe_u32 v8, v18, 16, 1
	ds_read2_b32 v[38:39], v23 offset0:198 offset1:206
	v_lshrrev_b32_e32 v7, 16, v7
	v_add3_u32 v8, v18, v8, s26
	ds_read2_b32 v[40:41], v23 offset0:231 offset1:239
	v_and_or_b32 v7, v8, s27, v7
	s_waitcnt lgkmcnt(3)
	v_bfe_u32 v8, v20, 16, 1
	v_add3_u32 v8, v20, v8, s26
	s_waitcnt lgkmcnt(2)
	v_bfe_u32 v9, v36, 16, 1
	v_lshrrev_b32_e32 v8, 16, v8
	v_add3_u32 v9, v36, v9, s26
	v_and_or_b32 v8, v9, s27, v8
	s_waitcnt lgkmcnt(1)
	v_bfe_u32 v9, v38, 16, 1
	v_add3_u32 v9, v38, v9, s26
	s_waitcnt lgkmcnt(0)
	v_bfe_u32 v10, v40, 16, 1
	v_lshrrev_b32_e32 v9, 16, v9
	v_add3_u32 v10, v40, v10, s26
	v_and_or_b32 v9, v10, s27, v9
	v_or_b32_e32 v10, s33, v22
	v_lshlrev_b32_e32 v42, 12, v10
	v_mov_b32_e32 v43, v3
	v_lshl_add_u64 v[42:43], v[12:13], 0, v[42:43]
	global_store_dwordx4 v[42:43], v[6:9], off nt
	v_bfe_u32 v10, v41, 16, 1
	v_add3_u32 v10, v41, v10, s26
	v_bfe_u32 v6, v11, 16, 1
	v_add3_u32 v6, v11, v6, s26
	v_bfe_u32 v7, v15, 16, 1
	v_lshrrev_b32_e32 v6, 16, v6
	v_add3_u32 v7, v15, v7, s26
	v_and_or_b32 v6, v7, s27, v6
	v_bfe_u32 v7, v17, 16, 1
	v_add3_u32 v7, v17, v7, s26
	v_bfe_u32 v8, v19, 16, 1
	v_lshrrev_b32_e32 v7, 16, v7
	v_add3_u32 v8, v19, v8, s26
	v_and_or_b32 v7, v8, s27, v7
	v_bfe_u32 v8, v21, 16, 1
	v_add3_u32 v8, v21, v8, s26
	v_bfe_u32 v9, v37, 16, 1
	v_lshrrev_b32_e32 v8, 16, v8
	v_add3_u32 v9, v37, v9, s26
	v_and_or_b32 v8, v9, s27, v8
	v_bfe_u32 v9, v39, 16, 1
	v_add3_u32 v9, v39, v9, s26
	v_lshrrev_b32_e32 v9, 16, v9
	v_and_or_b32 v9, v10, s27, v9
	v_or_b32_e32 v10, s33, v24
	v_lshlrev_b32_e32 v10, 12, v10
	v_mov_b32_e32 v11, v3
	ds_read2_b32 v[14:15], v23 offset0:16 offset1:24
	v_lshl_add_u64 v[10:11], v[12:13], 0, v[10:11]
	global_store_dwordx4 v[10:11], v[6:9], off nt
	ds_read2_b32 v[10:11], v23 offset0:49 offset1:57
	ds_read2_b32 v[16:17], v23 offset0:82 offset1:90
	ds_read2_b32 v[18:19], v23 offset0:115 offset1:123
	s_waitcnt lgkmcnt(3)
	v_bfe_u32 v6, v14, 16, 1
	v_add3_u32 v6, v14, v6, s26
	s_waitcnt lgkmcnt(2)
	v_bfe_u32 v7, v10, 16, 1
	ds_read2_b32 v[20:21], v23 offset0:148 offset1:156
	v_lshrrev_b32_e32 v6, 16, v6
	v_add3_u32 v7, v10, v7, s26
	ds_read2_b32 v[36:37], v23 offset0:181 offset1:189
	v_and_or_b32 v6, v7, s27, v6
	s_waitcnt lgkmcnt(3)
	v_bfe_u32 v7, v16, 16, 1
	v_add3_u32 v7, v16, v7, s26
	s_waitcnt lgkmcnt(2)
	v_bfe_u32 v8, v18, 16, 1
	ds_read2_b32 v[38:39], v23 offset0:214 offset1:222
	v_lshrrev_b32_e32 v7, 16, v7
	v_add3_u32 v8, v18, v8, s26
	ds_read2_b32 v[40:41], v23 offset0:247 offset1:255
	v_and_or_b32 v7, v8, s27, v7
	s_waitcnt lgkmcnt(3)
	v_bfe_u32 v8, v20, 16, 1
	v_add3_u32 v8, v20, v8, s26
	s_waitcnt lgkmcnt(2)
	v_bfe_u32 v9, v36, 16, 1
	v_lshrrev_b32_e32 v8, 16, v8
	v_add3_u32 v9, v36, v9, s26
	v_and_or_b32 v8, v9, s27, v8
	s_waitcnt lgkmcnt(1)
	v_bfe_u32 v9, v38, 16, 1
	v_add3_u32 v9, v38, v9, s26
	s_waitcnt lgkmcnt(0)
	v_bfe_u32 v10, v40, 16, 1
	v_lshrrev_b32_e32 v9, 16, v9
	v_add3_u32 v10, v40, v10, s26
	v_and_or_b32 v9, v10, s27, v9
	v_or_b32_e32 v10, s33, v25
	v_lshlrev_b32_e32 v42, 12, v10
	v_mov_b32_e32 v43, v3
	v_lshl_add_u64 v[42:43], v[12:13], 0, v[42:43]
	global_store_dwordx4 v[42:43], v[6:9], off nt
	v_bfe_u32 v10, v41, 16, 1
	v_add3_u32 v10, v41, v10, s26
	v_bfe_u32 v6, v15, 16, 1
	v_add3_u32 v6, v15, v6, s26
	v_bfe_u32 v7, v11, 16, 1
	v_lshrrev_b32_e32 v6, 16, v6
	v_add3_u32 v7, v11, v7, s26
	v_and_or_b32 v6, v7, s27, v6
	v_bfe_u32 v7, v17, 16, 1
	v_add3_u32 v7, v17, v7, s26
	v_bfe_u32 v8, v19, 16, 1
	v_lshrrev_b32_e32 v7, 16, v7
	v_add3_u32 v8, v19, v8, s26
	v_and_or_b32 v7, v8, s27, v7
	v_bfe_u32 v8, v21, 16, 1
	v_add3_u32 v8, v21, v8, s26
	v_bfe_u32 v9, v37, 16, 1
	v_lshrrev_b32_e32 v8, 16, v8
	v_add3_u32 v9, v37, v9, s26
	v_and_or_b32 v8, v9, s27, v8
	v_bfe_u32 v9, v39, 16, 1
	v_add3_u32 v9, v39, v9, s26
	v_lshrrev_b32_e32 v9, 16, v9
	v_and_or_b32 v9, v10, s27, v9
	v_or_b32_e32 v10, s33, v26
	v_lshlrev_b32_e32 v10, 12, v10
	v_mov_b32_e32 v11, v3
	v_lshl_add_u64 v[10:11], v[12:13], 0, v[10:11]
	global_store_dwordx4 v[10:11], v[6:9], off nt
	s_waitcnt lgkmcnt(0)

.LBB0_34:
	v_lshl_add_u64 v[36:37], v[20:21], 0, s[20:21]
	v_lshl_add_u64 v[38:39], v[18:19], 0, s[20:21]
	v_lshl_add_u64 v[40:41], v[16:17], 0, s[20:21]
	v_lshl_add_u64 v[42:43], v[14:15], 0, s[20:21]
	v_lshl_add_u64 v[44:45], v[12:13], 0, s[20:21]
	v_lshl_add_u64 v[46:47], v[10:11], 0, s[20:21]
	v_lshl_add_u64 v[48:49], v[8:9], 0, s[20:21]
	v_lshl_add_u64 v[50:51], v[6:7], 0, s[20:21]
	global_load_dword v52, v[36:37], off nt
	global_load_dword v53, v[38:39], off nt
	global_load_dword v54, v[40:41], off nt
	global_load_dword v55, v[42:43], off nt
	global_load_dword v56, v[44:45], off nt
	global_load_dword v57, v[46:47], off nt
	global_load_dword v58, v[48:49], off nt
	global_load_dword v59, v[50:51], off nt
	s_add_u32 s20, s20, 0x8000
	s_addc_u32 s21, s21, 0
	v_lshl_add_u64 v[36:37], v[20:21], 0, s[20:21]
	v_lshl_add_u64 v[38:39], v[18:19], 0, s[20:21]
	v_lshl_add_u64 v[40:41], v[16:17], 0, s[20:21]
	v_lshl_add_u64 v[42:43], v[14:15], 0, s[20:21]
	v_lshl_add_u64 v[44:45], v[12:13], 0, s[20:21]
	v_lshl_add_u64 v[46:47], v[10:11], 0, s[20:21]
	v_lshl_add_u64 v[48:49], v[8:9], 0, s[20:21]
	v_lshl_add_u64 v[50:51], v[6:7], 0, s[20:21]
	global_load_dword v60, v[36:37], off nt
	global_load_dword v61, v[38:39], off nt
	global_load_dword v62, v[40:41], off nt
	global_load_dword v63, v[42:43], off nt
	global_load_dword v64, v[44:45], off nt
	global_load_dword v65, v[46:47], off nt
	global_load_dword v66, v[48:49], off nt
	global_load_dword v67, v[50:51], off nt
	s_add_u32 s20, s20, 0x8000
	s_addc_u32 s21, s21, 0
	v_lshl_add_u64 v[36:37], v[20:21], 0, s[20:21]
	v_lshl_add_u64 v[38:39], v[18:19], 0, s[20:21]
	v_lshl_add_u64 v[40:41], v[16:17], 0, s[20:21]
	v_lshl_add_u64 v[42:43], v[14:15], 0, s[20:21]
	v_lshl_add_u64 v[44:45], v[12:13], 0, s[20:21]
	v_lshl_add_u64 v[46:47], v[10:11], 0, s[20:21]
	v_lshl_add_u64 v[48:49], v[8:9], 0, s[20:21]
	v_lshl_add_u64 v[50:51], v[6:7], 0, s[20:21]
	global_load_dword v68, v[36:37], off nt
	global_load_dword v69, v[38:39], off nt
	global_load_dword v70, v[40:41], off nt
	global_load_dword v71, v[42:43], off nt
	global_load_dword v72, v[44:45], off nt
	global_load_dword v73, v[46:47], off nt
	global_load_dword v74, v[48:49], off nt
	global_load_dword v75, v[50:51], off nt
	s_add_u32 s20, s20, 0x8000
	s_addc_u32 s21, s21, 0
	v_lshl_add_u64 v[36:37], v[20:21], 0, s[20:21]
	v_lshl_add_u64 v[38:39], v[18:19], 0, s[20:21]
	v_lshl_add_u64 v[40:41], v[16:17], 0, s[20:21]
	v_lshl_add_u64 v[42:43], v[14:15], 0, s[20:21]
	v_lshl_add_u64 v[44:45], v[12:13], 0, s[20:21]
	v_lshl_add_u64 v[46:47], v[10:11], 0, s[20:21]
	v_lshl_add_u64 v[48:49], v[8:9], 0, s[20:21]
	v_lshl_add_u64 v[50:51], v[6:7], 0, s[20:21]
	global_load_dword v76, v[36:37], off nt
	global_load_dword v77, v[38:39], off nt
	global_load_dword v78, v[40:41], off nt
	global_load_dword v79, v[42:43], off nt
	global_load_dword v80, v[44:45], off nt
	global_load_dword v81, v[46:47], off nt
	global_load_dword v82, v[48:49], off nt
	global_load_dword v83, v[50:51], off nt
	s_add_u32 s20, s20, 0x8000
	s_addc_u32 s21, s21, 0
	v_add_u32_e32 v36, 0x400, v35
	s_waitcnt vmcnt(30)
	ds_write2_b32 v35, v52, v53 offset1:66
	s_waitcnt vmcnt(28)
	ds_write2_b32 v35, v54, v55 offset0:132 offset1:198
	s_waitcnt vmcnt(26)
	ds_write2_b32 v36, v56, v57 offset0:8 offset1:74
	s_waitcnt vmcnt(24)
	ds_write2_b32 v36, v58, v59 offset0:140 offset1:206
	v_add_u32_e32 v35, 0x840, v35
	v_add_u32_e32 v36, 0x400, v35
	s_waitcnt vmcnt(22)
	ds_write2_b32 v35, v60, v61 offset1:66
	s_waitcnt vmcnt(20)
	ds_write2_b32 v35, v62, v63 offset0:132 offset1:198
	s_waitcnt vmcnt(18)
	ds_write2_b32 v36, v64, v65 offset0:8 offset1:74
	s_waitcnt vmcnt(16)
	ds_write2_b32 v36, v66, v67 offset0:140 offset1:206
	v_add_u32_e32 v35, 0x840, v35
	v_add_u32_e32 v36, 0x400, v35
	s_waitcnt vmcnt(14)
	ds_write2_b32 v35, v68, v69 offset1:66
	s_waitcnt vmcnt(12)
	ds_write2_b32 v35, v70, v71 offset0:132 offset1:198
	s_waitcnt vmcnt(10)
	ds_write2_b32 v36, v72, v73 offset0:8 offset1:74
	s_waitcnt vmcnt(8)
	ds_write2_b32 v36, v74, v75 offset0:140 offset1:206
	v_add_u32_e32 v35, 0x840, v35
	v_add_u32_e32 v36, 0x400, v35
	s_waitcnt vmcnt(6)
	ds_write2_b32 v35, v76, v77 offset1:66
	s_waitcnt vmcnt(4)
	ds_write2_b32 v35, v78, v79 offset0:132 offset1:198
	s_waitcnt vmcnt(2)
	ds_write2_b32 v36, v80, v81 offset0:8 offset1:74
	s_waitcnt vmcnt(0)
	ds_write2_b32 v36, v82, v83 offset0:140 offset1:206
	v_add_u32_e32 v35, 0x840, v35
	s_waitcnt lgkmcnt(0)
	s_lshl_b32 s20, s22, 5
	ds_read2_b32 v[10:11], v23 offset1:8
	s_and_b32 s33, s20, 0x1e0
	s_lshl_b32 s20, s23, 1
	ds_read2_b32 v[14:15], v23 offset0:33 offset1:41
	s_add_u32 s20, s30, s20
	s_addc_u32 s21, s31, 0
	ds_read2_b32 v[16:17], v23 offset0:66 offset1:74
	v_lshl_add_u64 v[6:7], s[20:21], 0, v[2:3]
	ds_read2_b32 v[18:19], v23 offset0:99 offset1:107
	v_lshl_add_u64 v[12:13], v[6:7], 0, s[38:39]
	s_waitcnt lgkmcnt(3)
	v_bfe_u32 v6, v10, 16, 1
	v_add3_u32 v6, v10, v6, s26
	s_waitcnt lgkmcnt(2)
	v_bfe_u32 v7, v14, 16, 1
	ds_read2_b32 v[20:21], v23 offset0:132 offset1:140
	v_lshrrev_b32_e32 v6, 16, v6
	v_add3_u32 v7, v14, v7, s26
	ds_read2_b32 v[36:37], v23 offset0:165 offset1:173
	v_and_or_b32 v6, v7, s27, v6
	s_waitcnt lgkmcnt(3)
	v_bfe_u32 v7, v16, 16, 1
	v_add3_u32 v7, v16, v7, s26
	s_waitcnt lgkmcnt(2)
	v_bfe_u32 v8, v18, 16, 1
	ds_read2_b32 v[38:39], v23 offset0:198 offset1:206
	v_lshrrev_b32_e32 v7, 16, v7
	v_add3_u32 v8, v18, v8, s26
	ds_read2_b32 v[40:41], v23 offset0:231 offset1:239
	v_and_or_b32 v7, v8, s27, v7
	s_waitcnt lgkmcnt(3)
	v_bfe_u32 v8, v20, 16, 1
	v_add3_u32 v8, v20, v8, s26
	s_waitcnt lgkmcnt(2)
	v_bfe_u32 v9, v36, 16, 1
	v_lshrrev_b32_e32 v8, 16, v8
	v_add3_u32 v9, v36, v9, s26
	v_and_or_b32 v8, v9, s27, v8
	s_waitcnt lgkmcnt(1)
	v_bfe_u32 v9, v38, 16, 1
	v_add3_u32 v9, v38, v9, s26
	s_waitcnt lgkmcnt(0)
	v_bfe_u32 v10, v40, 16, 1
	v_lshrrev_b32_e32 v9, 16, v9
	v_add3_u32 v10, v40, v10, s26
	v_and_or_b32 v9, v10, s27, v9
	v_or_b32_e32 v10, s33, v22
	v_lshlrev_b32_e32 v42, 10, v10
	v_mov_b32_e32 v43, v3
	v_lshl_add_u64 v[42:43], v[12:13], 0, v[42:43]
	global_store_dwordx4 v[42:43], v[6:9], off nt
	v_bfe_u32 v10, v41, 16, 1
	v_add3_u32 v10, v41, v10, s26
	v_bfe_u32 v6, v11, 16, 1
	v_add3_u32 v6, v11, v6, s26
	v_bfe_u32 v7, v15, 16, 1
	v_lshrrev_b32_e32 v6, 16, v6
	v_add3_u32 v7, v15, v7, s26
	v_and_or_b32 v6, v7, s27, v6
	v_bfe_u32 v7, v17, 16, 1
	v_add3_u32 v7, v17, v7, s26
	v_bfe_u32 v8, v19, 16, 1
	v_lshrrev_b32_e32 v7, 16, v7
	v_add3_u32 v8, v19, v8, s26
	v_and_or_b32 v7, v8, s27, v7
	v_bfe_u32 v8, v21, 16, 1
	v_add3_u32 v8, v21, v8, s26
	v_bfe_u32 v9, v37, 16, 1
	v_lshrrev_b32_e32 v8, 16, v8
	v_add3_u32 v9, v37, v9, s26
	v_and_or_b32 v8, v9, s27, v8
	v_bfe_u32 v9, v39, 16, 1
	v_add3_u32 v9, v39, v9, s26
	v_lshrrev_b32_e32 v9, 16, v9
	v_and_or_b32 v9, v10, s27, v9
	v_or_b32_e32 v10, s33, v24
	v_lshlrev_b32_e32 v10, 10, v10
	v_mov_b32_e32 v11, v3
	ds_read2_b32 v[14:15], v23 offset0:16 offset1:24
	v_lshl_add_u64 v[10:11], v[12:13], 0, v[10:11]
	global_store_dwordx4 v[10:11], v[6:9], off nt
	ds_read2_b32 v[10:11], v23 offset0:49 offset1:57
	ds_read2_b32 v[16:17], v23 offset0:82 offset1:90
	ds_read2_b32 v[18:19], v23 offset0:115 offset1:123
	s_waitcnt lgkmcnt(3)
	v_bfe_u32 v6, v14, 16, 1
	v_add3_u32 v6, v14, v6, s26
	s_waitcnt lgkmcnt(2)
	v_bfe_u32 v7, v10, 16, 1
	ds_read2_b32 v[20:21], v23 offset0:148 offset1:156
	v_lshrrev_b32_e32 v6, 16, v6
	v_add3_u32 v7, v10, v7, s26
	ds_read2_b32 v[36:37], v23 offset0:181 offset1:189
	v_and_or_b32 v6, v7, s27, v6
	s_waitcnt lgkmcnt(3)
	v_bfe_u32 v7, v16, 16, 1
	v_add3_u32 v7, v16, v7, s26
	s_waitcnt lgkmcnt(2)
	v_bfe_u32 v8, v18, 16, 1
	ds_read2_b32 v[38:39], v23 offset0:214 offset1:222
	v_lshrrev_b32_e32 v7, 16, v7
	v_add3_u32 v8, v18, v8, s26
	ds_read2_b32 v[40:41], v23 offset0:247 offset1:255
	v_and_or_b32 v7, v8, s27, v7
	s_waitcnt lgkmcnt(3)
	v_bfe_u32 v8, v20, 16, 1
	v_add3_u32 v8, v20, v8, s26
	s_waitcnt lgkmcnt(2)
	v_bfe_u32 v9, v36, 16, 1
	v_lshrrev_b32_e32 v8, 16, v8
	v_add3_u32 v9, v36, v9, s26
	v_and_or_b32 v8, v9, s27, v8
	s_waitcnt lgkmcnt(1)
	v_bfe_u32 v9, v38, 16, 1
	v_add3_u32 v9, v38, v9, s26
	s_waitcnt lgkmcnt(0)
	v_bfe_u32 v10, v40, 16, 1
	v_lshrrev_b32_e32 v9, 16, v9
	v_add3_u32 v10, v40, v10, s26
	v_and_or_b32 v9, v10, s27, v9
	v_or_b32_e32 v10, s33, v25
	v_lshlrev_b32_e32 v42, 10, v10
	v_mov_b32_e32 v43, v3
	v_lshl_add_u64 v[42:43], v[12:13], 0, v[42:43]
	global_store_dwordx4 v[42:43], v[6:9], off nt
	v_bfe_u32 v10, v41, 16, 1
	v_add3_u32 v10, v41, v10, s26
	v_bfe_u32 v6, v15, 16, 1
	v_add3_u32 v6, v15, v6, s26
	v_bfe_u32 v7, v11, 16, 1
	v_lshrrev_b32_e32 v6, 16, v6
	v_add3_u32 v7, v11, v7, s26
	v_and_or_b32 v6, v7, s27, v6
	v_bfe_u32 v7, v17, 16, 1
	v_add3_u32 v7, v17, v7, s26
	v_bfe_u32 v8, v19, 16, 1
	v_lshrrev_b32_e32 v7, 16, v7
	v_add3_u32 v8, v19, v8, s26
	v_and_or_b32 v7, v8, s27, v7
	v_bfe_u32 v8, v21, 16, 1
	v_add3_u32 v8, v21, v8, s26
	v_bfe_u32 v9, v37, 16, 1
	v_lshrrev_b32_e32 v8, 16, v8
	v_add3_u32 v9, v37, v9, s26
	v_and_or_b32 v8, v9, s27, v8
	v_bfe_u32 v9, v39, 16, 1
	v_add3_u32 v9, v39, v9, s26
	v_lshrrev_b32_e32 v9, 16, v9
	v_and_or_b32 v9, v10, s27, v9
	v_or_b32_e32 v10, s33, v26
	v_lshlrev_b32_e32 v10, 10, v10
	v_mov_b32_e32 v11, v3
	v_lshl_add_u64 v[10:11], v[12:13], 0, v[10:11]
	global_store_dwordx4 v[10:11], v[6:9], off nt
	s_waitcnt lgkmcnt(0)

.LBB0_39:
	v_lshl_add_u64 v[36:37], v[20:21], 0, s[20:21]
	v_lshl_add_u64 v[38:39], v[18:19], 0, s[20:21]
	v_lshl_add_u64 v[40:41], v[16:17], 0, s[20:21]
	v_lshl_add_u64 v[42:43], v[14:15], 0, s[20:21]
	v_lshl_add_u64 v[44:45], v[12:13], 0, s[20:21]
	v_lshl_add_u64 v[46:47], v[10:11], 0, s[20:21]
	v_lshl_add_u64 v[48:49], v[8:9], 0, s[20:21]
	v_lshl_add_u64 v[50:51], v[6:7], 0, s[20:21]
	global_load_dword v52, v[36:37], off nt
	global_load_dword v53, v[38:39], off nt
	global_load_dword v54, v[40:41], off nt
	global_load_dword v55, v[42:43], off nt
	global_load_dword v56, v[44:45], off nt
	global_load_dword v57, v[46:47], off nt
	global_load_dword v58, v[48:49], off nt
	global_load_dword v59, v[50:51], off nt
	s_add_u32 s20, s20, 0x20000
	s_addc_u32 s21, s21, 0
	v_lshl_add_u64 v[36:37], v[20:21], 0, s[20:21]
	v_lshl_add_u64 v[38:39], v[18:19], 0, s[20:21]
	v_lshl_add_u64 v[40:41], v[16:17], 0, s[20:21]
	v_lshl_add_u64 v[42:43], v[14:15], 0, s[20:21]
	v_lshl_add_u64 v[44:45], v[12:13], 0, s[20:21]
	v_lshl_add_u64 v[46:47], v[10:11], 0, s[20:21]
	v_lshl_add_u64 v[48:49], v[8:9], 0, s[20:21]
	v_lshl_add_u64 v[50:51], v[6:7], 0, s[20:21]
	global_load_dword v60, v[36:37], off nt
	global_load_dword v61, v[38:39], off nt
	global_load_dword v62, v[40:41], off nt
	global_load_dword v63, v[42:43], off nt
	global_load_dword v64, v[44:45], off nt
	global_load_dword v65, v[46:47], off nt
	global_load_dword v66, v[48:49], off nt
	global_load_dword v67, v[50:51], off nt
	s_add_u32 s20, s20, 0x20000
	s_addc_u32 s21, s21, 0
	v_lshl_add_u64 v[36:37], v[20:21], 0, s[20:21]
	v_lshl_add_u64 v[38:39], v[18:19], 0, s[20:21]
	v_lshl_add_u64 v[40:41], v[16:17], 0, s[20:21]
	v_lshl_add_u64 v[42:43], v[14:15], 0, s[20:21]
	v_lshl_add_u64 v[44:45], v[12:13], 0, s[20:21]
	v_lshl_add_u64 v[46:47], v[10:11], 0, s[20:21]
	v_lshl_add_u64 v[48:49], v[8:9], 0, s[20:21]
	v_lshl_add_u64 v[50:51], v[6:7], 0, s[20:21]
	global_load_dword v68, v[36:37], off nt
	global_load_dword v69, v[38:39], off nt
	global_load_dword v70, v[40:41], off nt
	global_load_dword v71, v[42:43], off nt
	global_load_dword v72, v[44:45], off nt
	global_load_dword v73, v[46:47], off nt
	global_load_dword v74, v[48:49], off nt
	global_load_dword v75, v[50:51], off nt
	s_add_u32 s20, s20, 0x20000
	s_addc_u32 s21, s21, 0
	v_lshl_add_u64 v[36:37], v[20:21], 0, s[20:21]
	v_lshl_add_u64 v[38:39], v[18:19], 0, s[20:21]
	v_lshl_add_u64 v[40:41], v[16:17], 0, s[20:21]
	v_lshl_add_u64 v[42:43], v[14:15], 0, s[20:21]
	v_lshl_add_u64 v[44:45], v[12:13], 0, s[20:21]
	v_lshl_add_u64 v[46:47], v[10:11], 0, s[20:21]
	v_lshl_add_u64 v[48:49], v[8:9], 0, s[20:21]
	v_lshl_add_u64 v[50:51], v[6:7], 0, s[20:21]
	global_load_dword v76, v[36:37], off nt
	global_load_dword v77, v[38:39], off nt
	global_load_dword v78, v[40:41], off nt
	global_load_dword v79, v[42:43], off nt
	global_load_dword v80, v[44:45], off nt
	global_load_dword v81, v[46:47], off nt
	global_load_dword v82, v[48:49], off nt
	global_load_dword v83, v[50:51], off nt
	s_add_u32 s20, s20, 0x20000
	s_addc_u32 s21, s21, 0
	v_add_u32_e32 v36, 0x400, v35
	s_waitcnt vmcnt(30)
	ds_write2_b32 v35, v52, v53 offset1:66
	s_waitcnt vmcnt(28)
	ds_write2_b32 v35, v54, v55 offset0:132 offset1:198
	s_waitcnt vmcnt(26)
	ds_write2_b32 v36, v56, v57 offset0:8 offset1:74
	s_waitcnt vmcnt(24)
	ds_write2_b32 v36, v58, v59 offset0:140 offset1:206
	v_add_u32_e32 v35, 0x840, v35
	v_add_u32_e32 v36, 0x400, v35
	s_waitcnt vmcnt(22)
	ds_write2_b32 v35, v60, v61 offset1:66
	s_waitcnt vmcnt(20)
	ds_write2_b32 v35, v62, v63 offset0:132 offset1:198
	s_waitcnt vmcnt(18)
	ds_write2_b32 v36, v64, v65 offset0:8 offset1:74
	s_waitcnt vmcnt(16)
	ds_write2_b32 v36, v66, v67 offset0:140 offset1:206
	v_add_u32_e32 v35, 0x840, v35
	v_add_u32_e32 v36, 0x400, v35
	s_waitcnt vmcnt(14)
	ds_write2_b32 v35, v68, v69 offset1:66
	s_waitcnt vmcnt(12)
	ds_write2_b32 v35, v70, v71 offset0:132 offset1:198
	s_waitcnt vmcnt(10)
	ds_write2_b32 v36, v72, v73 offset0:8 offset1:74
	s_waitcnt vmcnt(8)
	ds_write2_b32 v36, v74, v75 offset0:140 offset1:206
	v_add_u32_e32 v35, 0x840, v35
	v_add_u32_e32 v36, 0x400, v35
	s_waitcnt vmcnt(6)
	ds_write2_b32 v35, v76, v77 offset1:66
	s_waitcnt vmcnt(4)
	ds_write2_b32 v35, v78, v79 offset0:132 offset1:198
	s_waitcnt vmcnt(2)
	ds_write2_b32 v36, v80, v81 offset0:8 offset1:74
	s_waitcnt vmcnt(0)
	ds_write2_b32 v36, v82, v83 offset0:140 offset1:206
	v_add_u32_e32 v35, 0x840, v35
	s_waitcnt lgkmcnt(0)
	s_lshl_b32 s20, s22, 5
	ds_read2_b32 v[10:11], v23 offset1:8
	s_and_b32 s23, s20, 0x7e0
	s_lshl_b32 s19, s19, 1
	ds_read2_b32 v[14:15], v23 offset0:33 offset1:41
	s_add_u32 s20, s30, s19
	s_addc_u32 s21, s31, 0
	ds_read2_b32 v[16:17], v23 offset0:66 offset1:74
	v_lshl_add_u64 v[6:7], s[20:21], 0, v[2:3]
	ds_read2_b32 v[18:19], v23 offset0:99 offset1:107
	v_lshl_add_u64 v[12:13], v[6:7], 0, s[12:13]
	s_waitcnt lgkmcnt(3)
	v_bfe_u32 v6, v10, 16, 1
	v_add3_u32 v6, v10, v6, s26
	s_waitcnt lgkmcnt(2)
	v_bfe_u32 v7, v14, 16, 1
	ds_read2_b32 v[20:21], v23 offset0:132 offset1:140
	v_lshrrev_b32_e32 v6, 16, v6
	v_add3_u32 v7, v14, v7, s26
	ds_read2_b32 v[36:37], v23 offset0:165 offset1:173
	v_and_or_b32 v6, v7, s27, v6
	s_waitcnt lgkmcnt(3)
	v_bfe_u32 v7, v16, 16, 1
	v_add3_u32 v7, v16, v7, s26
	s_waitcnt lgkmcnt(2)
	v_bfe_u32 v8, v18, 16, 1
	ds_read2_b32 v[38:39], v23 offset0:198 offset1:206
	v_lshrrev_b32_e32 v7, 16, v7
	v_add3_u32 v8, v18, v8, s26
	ds_read2_b32 v[40:41], v23 offset0:231 offset1:239
	v_and_or_b32 v7, v8, s27, v7
	s_waitcnt lgkmcnt(3)
	v_bfe_u32 v8, v20, 16, 1
	v_add3_u32 v8, v20, v8, s26
	s_waitcnt lgkmcnt(2)
	v_bfe_u32 v9, v36, 16, 1
	v_lshrrev_b32_e32 v8, 16, v8
	v_add3_u32 v9, v36, v9, s26
	v_and_or_b32 v8, v9, s27, v8
	s_waitcnt lgkmcnt(1)
	v_bfe_u32 v9, v38, 16, 1
	v_add3_u32 v9, v38, v9, s26
	s_waitcnt lgkmcnt(0)
	v_bfe_u32 v10, v40, 16, 1
	v_lshrrev_b32_e32 v9, 16, v9
	v_add3_u32 v10, v40, v10, s26
	v_and_or_b32 v9, v10, s27, v9
	v_or_b32_e32 v10, s23, v22
	v_lshlrev_b32_e32 v42, 12, v10
	v_mov_b32_e32 v43, v3
	v_lshl_add_u64 v[42:43], v[12:13], 0, v[42:43]
	global_store_dwordx4 v[42:43], v[6:9], off nt
	v_bfe_u32 v10, v41, 16, 1
	v_add3_u32 v10, v41, v10, s26
	v_bfe_u32 v6, v11, 16, 1
	v_add3_u32 v6, v11, v6, s26
	v_bfe_u32 v7, v15, 16, 1
	v_lshrrev_b32_e32 v6, 16, v6
	v_add3_u32 v7, v15, v7, s26
	v_and_or_b32 v6, v7, s27, v6
	v_bfe_u32 v7, v17, 16, 1
	v_add3_u32 v7, v17, v7, s26
	v_bfe_u32 v8, v19, 16, 1
	v_lshrrev_b32_e32 v7, 16, v7
	v_add3_u32 v8, v19, v8, s26
	v_and_or_b32 v7, v8, s27, v7
	v_bfe_u32 v8, v21, 16, 1
	v_add3_u32 v8, v21, v8, s26
	v_bfe_u32 v9, v37, 16, 1
	v_lshrrev_b32_e32 v8, 16, v8
	v_add3_u32 v9, v37, v9, s26
	v_and_or_b32 v8, v9, s27, v8
	v_bfe_u32 v9, v39, 16, 1
	v_add3_u32 v9, v39, v9, s26
	v_lshrrev_b32_e32 v9, 16, v9
	v_and_or_b32 v9, v10, s27, v9
	v_or_b32_e32 v10, s23, v24
	v_lshlrev_b32_e32 v10, 12, v10
	v_mov_b32_e32 v11, v3
	ds_read2_b32 v[14:15], v23 offset0:16 offset1:24
	v_lshl_add_u64 v[10:11], v[12:13], 0, v[10:11]
	global_store_dwordx4 v[10:11], v[6:9], off nt
	ds_read2_b32 v[10:11], v23 offset0:49 offset1:57
	ds_read2_b32 v[16:17], v23 offset0:82 offset1:90
	ds_read2_b32 v[18:19], v23 offset0:115 offset1:123
	s_waitcnt lgkmcnt(3)
	v_bfe_u32 v6, v14, 16, 1
	v_add3_u32 v6, v14, v6, s26
	s_waitcnt lgkmcnt(2)
	v_bfe_u32 v7, v10, 16, 1
	ds_read2_b32 v[20:21], v23 offset0:148 offset1:156
	v_lshrrev_b32_e32 v6, 16, v6
	v_add3_u32 v7, v10, v7, s26
	ds_read2_b32 v[36:37], v23 offset0:181 offset1:189
	v_and_or_b32 v6, v7, s27, v6
	s_waitcnt lgkmcnt(3)
	v_bfe_u32 v7, v16, 16, 1
	v_add3_u32 v7, v16, v7, s26
	s_waitcnt lgkmcnt(2)
	v_bfe_u32 v8, v18, 16, 1
	ds_read2_b32 v[38:39], v23 offset0:214 offset1:222
	v_lshrrev_b32_e32 v7, 16, v7
	v_add3_u32 v8, v18, v8, s26
	ds_read2_b32 v[40:41], v23 offset0:247 offset1:255
	v_and_or_b32 v7, v8, s27, v7
	s_waitcnt lgkmcnt(3)
	v_bfe_u32 v8, v20, 16, 1
	v_add3_u32 v8, v20, v8, s26
	s_waitcnt lgkmcnt(2)
	v_bfe_u32 v9, v36, 16, 1
	v_lshrrev_b32_e32 v8, 16, v8
	v_add3_u32 v9, v36, v9, s26
	v_and_or_b32 v8, v9, s27, v8
	s_waitcnt lgkmcnt(1)
	v_bfe_u32 v9, v38, 16, 1
	v_add3_u32 v9, v38, v9, s26
	s_waitcnt lgkmcnt(0)
	v_bfe_u32 v10, v40, 16, 1
	v_lshrrev_b32_e32 v9, 16, v9
	v_add3_u32 v10, v40, v10, s26
	v_and_or_b32 v9, v10, s27, v9
	v_or_b32_e32 v10, s23, v25
	v_lshlrev_b32_e32 v42, 12, v10
	v_mov_b32_e32 v43, v3
	v_lshl_add_u64 v[42:43], v[12:13], 0, v[42:43]
	global_store_dwordx4 v[42:43], v[6:9], off nt
	v_bfe_u32 v10, v41, 16, 1
	v_add3_u32 v10, v41, v10, s26
	v_bfe_u32 v6, v15, 16, 1
	v_add3_u32 v6, v15, v6, s26
	v_bfe_u32 v7, v11, 16, 1
	v_lshrrev_b32_e32 v6, 16, v6
	v_add3_u32 v7, v11, v7, s26
	v_and_or_b32 v6, v7, s27, v6
	v_bfe_u32 v7, v17, 16, 1
	v_add3_u32 v7, v17, v7, s26
	v_bfe_u32 v8, v19, 16, 1
	v_lshrrev_b32_e32 v7, 16, v7
	v_add3_u32 v8, v19, v8, s26
	v_and_or_b32 v7, v8, s27, v7
	v_bfe_u32 v8, v21, 16, 1
	v_add3_u32 v8, v21, v8, s26
	v_bfe_u32 v9, v37, 16, 1
	v_lshrrev_b32_e32 v8, 16, v8
	v_add3_u32 v9, v37, v9, s26
	v_and_or_b32 v8, v9, s27, v8
	v_bfe_u32 v9, v39, 16, 1
	v_add3_u32 v9, v39, v9, s26
	v_lshrrev_b32_e32 v9, 16, v9
	v_and_or_b32 v9, v10, s27, v9
	v_or_b32_e32 v10, s23, v26
	v_lshlrev_b32_e32 v10, 12, v10
	v_mov_b32_e32 v11, v3
	v_lshl_add_u64 v[10:11], v[12:13], 0, v[10:11]
	global_store_dwordx4 v[10:11], v[6:9], off nt
	s_waitcnt lgkmcnt(0)

.LBB0_44:
	v_lshl_add_u64 v[36:37], v[20:21], 0, s[20:21]
	v_lshl_add_u64 v[38:39], v[18:19], 0, s[20:21]
	v_lshl_add_u64 v[40:41], v[16:17], 0, s[20:21]
	v_lshl_add_u64 v[42:43], v[14:15], 0, s[20:21]
	v_lshl_add_u64 v[44:45], v[12:13], 0, s[20:21]
	v_lshl_add_u64 v[46:47], v[10:11], 0, s[20:21]
	v_lshl_add_u64 v[48:49], v[8:9], 0, s[20:21]
	v_lshl_add_u64 v[50:51], v[6:7], 0, s[20:21]
	global_load_dword v52, v[36:37], off nt
	global_load_dword v53, v[38:39], off nt
	global_load_dword v54, v[40:41], off nt
	global_load_dword v55, v[42:43], off nt
	global_load_dword v56, v[44:45], off nt
	global_load_dword v57, v[46:47], off nt
	global_load_dword v58, v[48:49], off nt
	global_load_dword v59, v[50:51], off nt
	s_add_u32 s20, s20, 0x50000
	s_addc_u32 s21, s21, 0
	v_lshl_add_u64 v[36:37], v[20:21], 0, s[20:21]
	v_lshl_add_u64 v[38:39], v[18:19], 0, s[20:21]
	v_lshl_add_u64 v[40:41], v[16:17], 0, s[20:21]
	v_lshl_add_u64 v[42:43], v[14:15], 0, s[20:21]
	v_lshl_add_u64 v[44:45], v[12:13], 0, s[20:21]
	v_lshl_add_u64 v[46:47], v[10:11], 0, s[20:21]
	v_lshl_add_u64 v[48:49], v[8:9], 0, s[20:21]
	v_lshl_add_u64 v[50:51], v[6:7], 0, s[20:21]
	global_load_dword v60, v[36:37], off nt
	global_load_dword v61, v[38:39], off nt
	global_load_dword v62, v[40:41], off nt
	global_load_dword v63, v[42:43], off nt
	global_load_dword v64, v[44:45], off nt
	global_load_dword v65, v[46:47], off nt
	global_load_dword v66, v[48:49], off nt
	global_load_dword v67, v[50:51], off nt
	s_add_u32 s20, s20, 0x50000
	s_addc_u32 s21, s21, 0
	v_lshl_add_u64 v[36:37], v[20:21], 0, s[20:21]
	v_lshl_add_u64 v[38:39], v[18:19], 0, s[20:21]
	v_lshl_add_u64 v[40:41], v[16:17], 0, s[20:21]
	v_lshl_add_u64 v[42:43], v[14:15], 0, s[20:21]
	v_lshl_add_u64 v[44:45], v[12:13], 0, s[20:21]
	v_lshl_add_u64 v[46:47], v[10:11], 0, s[20:21]
	v_lshl_add_u64 v[48:49], v[8:9], 0, s[20:21]
	v_lshl_add_u64 v[50:51], v[6:7], 0, s[20:21]
	global_load_dword v68, v[36:37], off nt
	global_load_dword v69, v[38:39], off nt
	global_load_dword v70, v[40:41], off nt
	global_load_dword v71, v[42:43], off nt
	global_load_dword v72, v[44:45], off nt
	global_load_dword v73, v[46:47], off nt
	global_load_dword v74, v[48:49], off nt
	global_load_dword v75, v[50:51], off nt
	s_add_u32 s20, s20, 0x50000
	s_addc_u32 s21, s21, 0
	v_lshl_add_u64 v[36:37], v[20:21], 0, s[20:21]
	v_lshl_add_u64 v[38:39], v[18:19], 0, s[20:21]
	v_lshl_add_u64 v[40:41], v[16:17], 0, s[20:21]
	v_lshl_add_u64 v[42:43], v[14:15], 0, s[20:21]
	v_lshl_add_u64 v[44:45], v[12:13], 0, s[20:21]
	v_lshl_add_u64 v[46:47], v[10:11], 0, s[20:21]
	v_lshl_add_u64 v[48:49], v[8:9], 0, s[20:21]
	v_lshl_add_u64 v[50:51], v[6:7], 0, s[20:21]
	global_load_dword v76, v[36:37], off nt
	global_load_dword v77, v[38:39], off nt
	global_load_dword v78, v[40:41], off nt
	global_load_dword v79, v[42:43], off nt
	global_load_dword v80, v[44:45], off nt
	global_load_dword v81, v[46:47], off nt
	global_load_dword v82, v[48:49], off nt
	global_load_dword v83, v[50:51], off nt
	s_add_u32 s20, s20, 0x50000
	s_addc_u32 s21, s21, 0
	v_add_u32_e32 v36, 0x400, v35
	s_waitcnt vmcnt(30)
	ds_write2_b32 v35, v52, v53 offset1:66
	s_waitcnt vmcnt(28)
	ds_write2_b32 v35, v54, v55 offset0:132 offset1:198
	s_waitcnt vmcnt(26)
	ds_write2_b32 v36, v56, v57 offset0:8 offset1:74
	s_waitcnt vmcnt(24)
	ds_write2_b32 v36, v58, v59 offset0:140 offset1:206
	v_add_u32_e32 v35, 0x840, v35
	v_add_u32_e32 v36, 0x400, v35
	s_waitcnt vmcnt(22)
	ds_write2_b32 v35, v60, v61 offset1:66
	s_waitcnt vmcnt(20)
	ds_write2_b32 v35, v62, v63 offset0:132 offset1:198
	s_waitcnt vmcnt(18)
	ds_write2_b32 v36, v64, v65 offset0:8 offset1:74
	s_waitcnt vmcnt(16)
	ds_write2_b32 v36, v66, v67 offset0:140 offset1:206
	v_add_u32_e32 v35, 0x840, v35
	v_add_u32_e32 v36, 0x400, v35
	s_waitcnt vmcnt(14)
	ds_write2_b32 v35, v68, v69 offset1:66
	s_waitcnt vmcnt(12)
	ds_write2_b32 v35, v70, v71 offset0:132 offset1:198
	s_waitcnt vmcnt(10)
	ds_write2_b32 v36, v72, v73 offset0:8 offset1:74
	s_waitcnt vmcnt(8)
	ds_write2_b32 v36, v74, v75 offset0:140 offset1:206
	v_add_u32_e32 v35, 0x840, v35
	v_add_u32_e32 v36, 0x400, v35
	s_waitcnt vmcnt(6)
	ds_write2_b32 v35, v76, v77 offset1:66
	s_waitcnt vmcnt(4)
	ds_write2_b32 v35, v78, v79 offset0:132 offset1:198
	s_waitcnt vmcnt(2)
	ds_write2_b32 v36, v80, v81 offset0:8 offset1:74
	s_waitcnt vmcnt(0)
	ds_write2_b32 v36, v82, v83 offset0:140 offset1:206
	v_add_u32_e32 v35, 0x840, v35
	s_waitcnt lgkmcnt(0)
	s_and_b32 s19, 0xffff, s19
	ds_read2_b32 v[10:11], v23 offset1:8
	s_and_b32 s23, 0xffff, s23
	s_lshl_b32 s19, s19, 1
	ds_read2_b32 v[14:15], v23 offset0:33 offset1:41
	s_add_u32 s20, s30, s19
	s_addc_u32 s21, s31, 0
	ds_read2_b32 v[16:17], v23 offset0:66 offset1:74
	v_lshl_add_u64 v[6:7], s[20:21], 0, v[2:3]
	ds_read2_b32 v[18:19], v23 offset0:99 offset1:107
	v_lshl_add_u64 v[12:13], v[6:7], 0, s[14:15]
	s_waitcnt lgkmcnt(3)
	v_bfe_u32 v6, v10, 16, 1
	v_add3_u32 v6, v10, v6, s26
	s_waitcnt lgkmcnt(2)
	v_bfe_u32 v7, v14, 16, 1
	ds_read2_b32 v[20:21], v23 offset0:132 offset1:140
	v_lshrrev_b32_e32 v6, 16, v6
	v_add3_u32 v7, v14, v7, s26
	ds_read2_b32 v[36:37], v23 offset0:165 offset1:173
	v_and_or_b32 v6, v7, s27, v6
	s_waitcnt lgkmcnt(3)
	v_bfe_u32 v7, v16, 16, 1
	v_add3_u32 v7, v16, v7, s26
	s_waitcnt lgkmcnt(2)
	v_bfe_u32 v8, v18, 16, 1
	ds_read2_b32 v[38:39], v23 offset0:198 offset1:206
	v_lshrrev_b32_e32 v7, 16, v7
	v_add3_u32 v8, v18, v8, s26
	ds_read2_b32 v[40:41], v23 offset0:231 offset1:239
	v_and_or_b32 v7, v8, s27, v7
	s_waitcnt lgkmcnt(3)
	v_bfe_u32 v8, v20, 16, 1
	v_add3_u32 v8, v20, v8, s26
	s_waitcnt lgkmcnt(2)
	v_bfe_u32 v9, v36, 16, 1
	v_lshrrev_b32_e32 v8, 16, v8
	v_add3_u32 v9, v36, v9, s26
	v_and_or_b32 v8, v9, s27, v8
	s_waitcnt lgkmcnt(1)
	v_bfe_u32 v9, v38, 16, 1
	v_add3_u32 v9, v38, v9, s26
	s_waitcnt lgkmcnt(0)
	v_bfe_u32 v10, v40, 16, 1
	v_lshrrev_b32_e32 v9, 16, v9
	v_add3_u32 v10, v40, v10, s26
	v_and_or_b32 v9, v10, s27, v9
	v_or_b32_e32 v10, s23, v22
	v_lshlrev_b32_e32 v42, 12, v10
	v_mov_b32_e32 v43, v3
	v_lshl_add_u64 v[42:43], v[12:13], 0, v[42:43]
	global_store_dwordx4 v[42:43], v[6:9], off nt
	v_bfe_u32 v10, v41, 16, 1
	v_add3_u32 v10, v41, v10, s26
	v_bfe_u32 v6, v11, 16, 1
	v_add3_u32 v6, v11, v6, s26
	v_bfe_u32 v7, v15, 16, 1
	v_lshrrev_b32_e32 v6, 16, v6
	v_add3_u32 v7, v15, v7, s26
	v_and_or_b32 v6, v7, s27, v6
	v_bfe_u32 v7, v17, 16, 1
	v_add3_u32 v7, v17, v7, s26
	v_bfe_u32 v8, v19, 16, 1
	v_lshrrev_b32_e32 v7, 16, v7
	v_add3_u32 v8, v19, v8, s26
	v_and_or_b32 v7, v8, s27, v7
	v_bfe_u32 v8, v21, 16, 1
	v_add3_u32 v8, v21, v8, s26
	v_bfe_u32 v9, v37, 16, 1
	v_lshrrev_b32_e32 v8, 16, v8
	v_add3_u32 v9, v37, v9, s26
	v_and_or_b32 v8, v9, s27, v8
	v_bfe_u32 v9, v39, 16, 1
	v_add3_u32 v9, v39, v9, s26
	v_lshrrev_b32_e32 v9, 16, v9
	v_and_or_b32 v9, v10, s27, v9
	v_or_b32_e32 v10, s23, v24
	v_lshlrev_b32_e32 v10, 12, v10
	v_mov_b32_e32 v11, v3
	ds_read2_b32 v[14:15], v23 offset0:16 offset1:24
	v_lshl_add_u64 v[10:11], v[12:13], 0, v[10:11]
	global_store_dwordx4 v[10:11], v[6:9], off nt
	ds_read2_b32 v[10:11], v23 offset0:49 offset1:57
	ds_read2_b32 v[16:17], v23 offset0:82 offset1:90
	ds_read2_b32 v[18:19], v23 offset0:115 offset1:123
	s_waitcnt lgkmcnt(3)
	v_bfe_u32 v6, v14, 16, 1
	v_add3_u32 v6, v14, v6, s26
	s_waitcnt lgkmcnt(2)
	v_bfe_u32 v7, v10, 16, 1
	ds_read2_b32 v[20:21], v23 offset0:148 offset1:156
	v_lshrrev_b32_e32 v6, 16, v6
	v_add3_u32 v7, v10, v7, s26
	ds_read2_b32 v[36:37], v23 offset0:181 offset1:189
	v_and_or_b32 v6, v7, s27, v6
	s_waitcnt lgkmcnt(3)
	v_bfe_u32 v7, v16, 16, 1
	v_add3_u32 v7, v16, v7, s26
	s_waitcnt lgkmcnt(2)
	v_bfe_u32 v8, v18, 16, 1
	ds_read2_b32 v[38:39], v23 offset0:214 offset1:222
	v_lshrrev_b32_e32 v7, 16, v7
	v_add3_u32 v8, v18, v8, s26
	ds_read2_b32 v[40:41], v23 offset0:247 offset1:255
	v_and_or_b32 v7, v8, s27, v7
	s_waitcnt lgkmcnt(3)
	v_bfe_u32 v8, v20, 16, 1
	v_add3_u32 v8, v20, v8, s26
	s_waitcnt lgkmcnt(2)
	v_bfe_u32 v9, v36, 16, 1
	v_lshrrev_b32_e32 v8, 16, v8
	v_add3_u32 v9, v36, v9, s26
	v_and_or_b32 v8, v9, s27, v8
	s_waitcnt lgkmcnt(1)
	v_bfe_u32 v9, v38, 16, 1
	v_add3_u32 v9, v38, v9, s26
	s_waitcnt lgkmcnt(0)
	v_bfe_u32 v10, v40, 16, 1
	v_lshrrev_b32_e32 v9, 16, v9
	v_add3_u32 v10, v40, v10, s26
	v_and_or_b32 v9, v10, s27, v9
	v_or_b32_e32 v10, s23, v25
	v_lshlrev_b32_e32 v42, 12, v10
	v_mov_b32_e32 v43, v3
	v_lshl_add_u64 v[42:43], v[12:13], 0, v[42:43]
	global_store_dwordx4 v[42:43], v[6:9], off nt
	v_bfe_u32 v10, v41, 16, 1
	v_add3_u32 v10, v41, v10, s26
	v_bfe_u32 v6, v15, 16, 1
	v_add3_u32 v6, v15, v6, s26
	v_bfe_u32 v7, v11, 16, 1
	v_lshrrev_b32_e32 v6, 16, v6
	v_add3_u32 v7, v11, v7, s26
	v_and_or_b32 v6, v7, s27, v6
	v_bfe_u32 v7, v17, 16, 1
	v_add3_u32 v7, v17, v7, s26
	v_bfe_u32 v8, v19, 16, 1
	v_lshrrev_b32_e32 v7, 16, v7
	v_add3_u32 v8, v19, v8, s26
	v_and_or_b32 v7, v8, s27, v7
	v_bfe_u32 v8, v21, 16, 1
	v_add3_u32 v8, v21, v8, s26
	v_bfe_u32 v9, v37, 16, 1
	v_lshrrev_b32_e32 v8, 16, v8
	v_add3_u32 v9, v37, v9, s26
	v_and_or_b32 v8, v9, s27, v8
	v_bfe_u32 v9, v39, 16, 1
	v_add3_u32 v9, v39, v9, s26
	v_lshrrev_b32_e32 v9, 16, v9
	v_and_or_b32 v9, v10, s27, v9
	v_or_b32_e32 v10, s23, v26
	v_lshlrev_b32_e32 v10, 12, v10
	v_mov_b32_e32 v11, v3
	v_lshl_add_u64 v[10:11], v[12:13], 0, v[10:11]
	global_store_dwordx4 v[10:11], v[6:9], off nt
	s_waitcnt lgkmcnt(0)

.LBB0_49:
	v_lshl_add_u64 v[36:37], v[20:21], 0, s[20:21]
	v_lshl_add_u64 v[38:39], v[18:19], 0, s[20:21]
	v_lshl_add_u64 v[40:41], v[16:17], 0, s[20:21]
	v_lshl_add_u64 v[42:43], v[14:15], 0, s[20:21]
	v_lshl_add_u64 v[44:45], v[12:13], 0, s[20:21]
	v_lshl_add_u64 v[46:47], v[10:11], 0, s[20:21]
	v_lshl_add_u64 v[48:49], v[8:9], 0, s[20:21]
	v_lshl_add_u64 v[50:51], v[6:7], 0, s[20:21]
	global_load_dword v52, v[36:37], off nt
	global_load_dword v53, v[38:39], off nt
	global_load_dword v54, v[40:41], off nt
	global_load_dword v55, v[42:43], off nt
	global_load_dword v56, v[44:45], off nt
	global_load_dword v57, v[46:47], off nt
	global_load_dword v58, v[48:49], off nt
	global_load_dword v59, v[50:51], off nt
	s_add_u32 s20, s20, 0x20000
	s_addc_u32 s21, s21, 0
	v_lshl_add_u64 v[36:37], v[20:21], 0, s[20:21]
	v_lshl_add_u64 v[38:39], v[18:19], 0, s[20:21]
	v_lshl_add_u64 v[40:41], v[16:17], 0, s[20:21]
	v_lshl_add_u64 v[42:43], v[14:15], 0, s[20:21]
	v_lshl_add_u64 v[44:45], v[12:13], 0, s[20:21]
	v_lshl_add_u64 v[46:47], v[10:11], 0, s[20:21]
	v_lshl_add_u64 v[48:49], v[8:9], 0, s[20:21]
	v_lshl_add_u64 v[50:51], v[6:7], 0, s[20:21]
	global_load_dword v60, v[36:37], off nt
	global_load_dword v61, v[38:39], off nt
	global_load_dword v62, v[40:41], off nt
	global_load_dword v63, v[42:43], off nt
	global_load_dword v64, v[44:45], off nt
	global_load_dword v65, v[46:47], off nt
	global_load_dword v66, v[48:49], off nt
	global_load_dword v67, v[50:51], off nt
	s_add_u32 s20, s20, 0x20000
	s_addc_u32 s21, s21, 0
	v_lshl_add_u64 v[36:37], v[20:21], 0, s[20:21]
	v_lshl_add_u64 v[38:39], v[18:19], 0, s[20:21]
	v_lshl_add_u64 v[40:41], v[16:17], 0, s[20:21]
	v_lshl_add_u64 v[42:43], v[14:15], 0, s[20:21]
	v_lshl_add_u64 v[44:45], v[12:13], 0, s[20:21]
	v_lshl_add_u64 v[46:47], v[10:11], 0, s[20:21]
	v_lshl_add_u64 v[48:49], v[8:9], 0, s[20:21]
	v_lshl_add_u64 v[50:51], v[6:7], 0, s[20:21]
	global_load_dword v68, v[36:37], off nt
	global_load_dword v69, v[38:39], off nt
	global_load_dword v70, v[40:41], off nt
	global_load_dword v71, v[42:43], off nt
	global_load_dword v72, v[44:45], off nt
	global_load_dword v73, v[46:47], off nt
	global_load_dword v74, v[48:49], off nt
	global_load_dword v75, v[50:51], off nt
	s_add_u32 s20, s20, 0x20000
	s_addc_u32 s21, s21, 0
	v_lshl_add_u64 v[36:37], v[20:21], 0, s[20:21]
	v_lshl_add_u64 v[38:39], v[18:19], 0, s[20:21]
	v_lshl_add_u64 v[40:41], v[16:17], 0, s[20:21]
	v_lshl_add_u64 v[42:43], v[14:15], 0, s[20:21]
	v_lshl_add_u64 v[44:45], v[12:13], 0, s[20:21]
	v_lshl_add_u64 v[46:47], v[10:11], 0, s[20:21]
	v_lshl_add_u64 v[48:49], v[8:9], 0, s[20:21]
	v_lshl_add_u64 v[50:51], v[6:7], 0, s[20:21]
	global_load_dword v76, v[36:37], off nt
	global_load_dword v77, v[38:39], off nt
	global_load_dword v78, v[40:41], off nt
	global_load_dword v79, v[42:43], off nt
	global_load_dword v80, v[44:45], off nt
	global_load_dword v81, v[46:47], off nt
	global_load_dword v82, v[48:49], off nt
	global_load_dword v83, v[50:51], off nt
	s_add_u32 s20, s20, 0x20000
	s_addc_u32 s21, s21, 0
	v_add_u32_e32 v36, 0x400, v35
	s_waitcnt vmcnt(30)
	ds_write2_b32 v35, v52, v53 offset1:66
	s_waitcnt vmcnt(28)
	ds_write2_b32 v35, v54, v55 offset0:132 offset1:198
	s_waitcnt vmcnt(26)
	ds_write2_b32 v36, v56, v57 offset0:8 offset1:74
	s_waitcnt vmcnt(24)
	ds_write2_b32 v36, v58, v59 offset0:140 offset1:206
	v_add_u32_e32 v35, 0x840, v35
	v_add_u32_e32 v36, 0x400, v35
	s_waitcnt vmcnt(22)
	ds_write2_b32 v35, v60, v61 offset1:66
	s_waitcnt vmcnt(20)
	ds_write2_b32 v35, v62, v63 offset0:132 offset1:198
	s_waitcnt vmcnt(18)
	ds_write2_b32 v36, v64, v65 offset0:8 offset1:74
	s_waitcnt vmcnt(16)
	ds_write2_b32 v36, v66, v67 offset0:140 offset1:206
	v_add_u32_e32 v35, 0x840, v35
	v_add_u32_e32 v36, 0x400, v35
	s_waitcnt vmcnt(14)
	ds_write2_b32 v35, v68, v69 offset1:66
	s_waitcnt vmcnt(12)
	ds_write2_b32 v35, v70, v71 offset0:132 offset1:198
	s_waitcnt vmcnt(10)
	ds_write2_b32 v36, v72, v73 offset0:8 offset1:74
	s_waitcnt vmcnt(8)
	ds_write2_b32 v36, v74, v75 offset0:140 offset1:206
	v_add_u32_e32 v35, 0x840, v35
	v_add_u32_e32 v36, 0x400, v35
	s_waitcnt vmcnt(6)
	ds_write2_b32 v35, v76, v77 offset1:66
	s_waitcnt vmcnt(4)
	ds_write2_b32 v35, v78, v79 offset0:132 offset1:198
	s_waitcnt vmcnt(2)
	ds_write2_b32 v36, v80, v81 offset0:8 offset1:74
	s_waitcnt vmcnt(0)
	ds_write2_b32 v36, v82, v83 offset0:140 offset1:206
	v_add_u32_e32 v35, 0x840, v35
	s_waitcnt lgkmcnt(0)
	s_lshl_b32 s20, s22, 5
	ds_read2_b32 v[10:11], v23 offset1:8
	s_and_b32 s23, s20, 0x7e0
	s_lshl_b32 s19, s19, 1
	ds_read2_b32 v[14:15], v23 offset0:33 offset1:41
	s_add_u32 s20, s30, s19
	s_addc_u32 s21, s31, 0
	ds_read2_b32 v[16:17], v23 offset0:66 offset1:74
	v_lshl_add_u64 v[6:7], s[20:21], 0, v[2:3]
	ds_read2_b32 v[18:19], v23 offset0:99 offset1:107
	v_lshl_add_u64 v[12:13], v[6:7], 0, s[16:17]
	s_waitcnt lgkmcnt(3)
	v_bfe_u32 v6, v10, 16, 1
	v_add3_u32 v6, v10, v6, s26
	s_waitcnt lgkmcnt(2)
	v_bfe_u32 v7, v14, 16, 1
	ds_read2_b32 v[20:21], v23 offset0:132 offset1:140
	v_lshrrev_b32_e32 v6, 16, v6
	v_add3_u32 v7, v14, v7, s26
	ds_read2_b32 v[36:37], v23 offset0:165 offset1:173
	v_and_or_b32 v6, v7, s27, v6
	s_waitcnt lgkmcnt(3)
	v_bfe_u32 v7, v16, 16, 1
	v_add3_u32 v7, v16, v7, s26
	s_waitcnt lgkmcnt(2)
	v_bfe_u32 v8, v18, 16, 1
	ds_read2_b32 v[38:39], v23 offset0:198 offset1:206
	v_lshrrev_b32_e32 v7, 16, v7
	v_add3_u32 v8, v18, v8, s26
	ds_read2_b32 v[40:41], v23 offset0:231 offset1:239
	v_and_or_b32 v7, v8, s27, v7
	s_waitcnt lgkmcnt(3)
	v_bfe_u32 v8, v20, 16, 1
	v_add3_u32 v8, v20, v8, s26
	s_waitcnt lgkmcnt(2)
	v_bfe_u32 v9, v36, 16, 1
	v_lshrrev_b32_e32 v8, 16, v8
	v_add3_u32 v9, v36, v9, s26
	v_and_or_b32 v8, v9, s27, v8
	s_waitcnt lgkmcnt(1)
	v_bfe_u32 v9, v38, 16, 1
	v_add3_u32 v9, v38, v9, s26
	s_waitcnt lgkmcnt(0)
	v_bfe_u32 v10, v40, 16, 1
	v_lshrrev_b32_e32 v9, 16, v9
	v_add3_u32 v10, v40, v10, s26
	v_and_or_b32 v9, v10, s27, v9
	v_or_b32_e32 v10, s23, v22
	v_mul_u32_u24_e32 v10, 0x1600, v10
	v_lshlrev_b32_e32 v42, 1, v10
	v_mov_b32_e32 v43, v3
	v_lshl_add_u64 v[42:43], v[12:13], 0, v[42:43]
	global_store_dwordx4 v[42:43], v[6:9], off nt
	v_bfe_u32 v10, v41, 16, 1
	v_add3_u32 v10, v41, v10, s26
	v_bfe_u32 v6, v11, 16, 1
	v_add3_u32 v6, v11, v6, s26
	v_bfe_u32 v7, v15, 16, 1
	v_lshrrev_b32_e32 v6, 16, v6
	v_add3_u32 v7, v15, v7, s26
	v_and_or_b32 v6, v7, s27, v6
	v_bfe_u32 v7, v17, 16, 1
	v_add3_u32 v7, v17, v7, s26
	v_bfe_u32 v8, v19, 16, 1
	v_lshrrev_b32_e32 v7, 16, v7
	v_add3_u32 v8, v19, v8, s26
	v_and_or_b32 v7, v8, s27, v7
	v_bfe_u32 v8, v21, 16, 1
	v_add3_u32 v8, v21, v8, s26
	v_bfe_u32 v9, v37, 16, 1
	v_lshrrev_b32_e32 v8, 16, v8
	v_add3_u32 v9, v37, v9, s26
	v_and_or_b32 v8, v9, s27, v8
	v_bfe_u32 v9, v39, 16, 1
	v_add3_u32 v9, v39, v9, s26
	v_lshrrev_b32_e32 v9, 16, v9
	v_and_or_b32 v9, v10, s27, v9
	v_or_b32_e32 v10, s23, v24
	v_mul_u32_u24_e32 v10, 0x1600, v10
	v_lshlrev_b32_e32 v10, 1, v10
	v_mov_b32_e32 v11, v3
	ds_read2_b32 v[14:15], v23 offset0:16 offset1:24
	v_lshl_add_u64 v[10:11], v[12:13], 0, v[10:11]
	global_store_dwordx4 v[10:11], v[6:9], off nt
	ds_read2_b32 v[10:11], v23 offset0:49 offset1:57
	ds_read2_b32 v[16:17], v23 offset0:82 offset1:90
	ds_read2_b32 v[18:19], v23 offset0:115 offset1:123
	s_waitcnt lgkmcnt(3)
	v_bfe_u32 v6, v14, 16, 1
	v_add3_u32 v6, v14, v6, s26
	s_waitcnt lgkmcnt(2)
	v_bfe_u32 v7, v10, 16, 1
	ds_read2_b32 v[20:21], v23 offset0:148 offset1:156
	v_lshrrev_b32_e32 v6, 16, v6
	v_add3_u32 v7, v10, v7, s26
	ds_read2_b32 v[36:37], v23 offset0:181 offset1:189
	v_and_or_b32 v6, v7, s27, v6
	s_waitcnt lgkmcnt(3)
	v_bfe_u32 v7, v16, 16, 1
	v_add3_u32 v7, v16, v7, s26
	s_waitcnt lgkmcnt(2)
	v_bfe_u32 v8, v18, 16, 1
	ds_read2_b32 v[38:39], v23 offset0:214 offset1:222
	v_lshrrev_b32_e32 v7, 16, v7
	v_add3_u32 v8, v18, v8, s26
	ds_read2_b32 v[40:41], v23 offset0:247 offset1:255
	v_and_or_b32 v7, v8, s27, v7
	s_waitcnt lgkmcnt(3)
	v_bfe_u32 v8, v20, 16, 1
	v_add3_u32 v8, v20, v8, s26
	s_waitcnt lgkmcnt(2)
	v_bfe_u32 v9, v36, 16, 1
	v_lshrrev_b32_e32 v8, 16, v8
	v_add3_u32 v9, v36, v9, s26
	v_and_or_b32 v8, v9, s27, v8
	s_waitcnt lgkmcnt(1)
	v_bfe_u32 v9, v38, 16, 1
	v_add3_u32 v9, v38, v9, s26
	s_waitcnt lgkmcnt(0)
	v_bfe_u32 v10, v40, 16, 1
	v_lshrrev_b32_e32 v9, 16, v9
	v_add3_u32 v10, v40, v10, s26
	v_and_or_b32 v9, v10, s27, v9
	v_or_b32_e32 v10, s23, v25
	v_mul_u32_u24_e32 v10, 0x1600, v10
	v_lshlrev_b32_e32 v42, 1, v10
	v_mov_b32_e32 v43, v3
	v_lshl_add_u64 v[42:43], v[12:13], 0, v[42:43]
	global_store_dwordx4 v[42:43], v[6:9], off nt
	v_bfe_u32 v10, v41, 16, 1
	v_add3_u32 v10, v41, v10, s26
	v_bfe_u32 v6, v15, 16, 1
	v_add3_u32 v6, v15, v6, s26
	v_bfe_u32 v7, v11, 16, 1
	v_lshrrev_b32_e32 v6, 16, v6
	v_add3_u32 v7, v11, v7, s26
	v_and_or_b32 v6, v7, s27, v6
	v_bfe_u32 v7, v17, 16, 1
	v_add3_u32 v7, v17, v7, s26
	v_bfe_u32 v8, v19, 16, 1
	v_lshrrev_b32_e32 v7, 16, v7
	v_add3_u32 v8, v19, v8, s26
	v_and_or_b32 v7, v8, s27, v7
	v_bfe_u32 v8, v21, 16, 1
	v_add3_u32 v8, v21, v8, s26
	v_bfe_u32 v9, v37, 16, 1
	v_lshrrev_b32_e32 v8, 16, v8
	v_add3_u32 v9, v37, v9, s26
	v_and_or_b32 v8, v9, s27, v8
	v_bfe_u32 v9, v39, 16, 1
	v_add3_u32 v9, v39, v9, s26
	v_lshrrev_b32_e32 v9, 16, v9
	v_and_or_b32 v9, v10, s27, v9
	v_or_b32_e32 v10, s23, v26
	v_mul_u32_u24_e32 v10, 0x1600, v10
	v_lshlrev_b32_e32 v10, 1, v10
	v_mov_b32_e32 v11, v3
	v_lshl_add_u64 v[10:11], v[12:13], 0, v[10:11]
	global_store_dwordx4 v[10:11], v[6:9], off nt
	s_waitcnt lgkmcnt(0)

.LBB0_54:
	v_lshl_add_u64 v[36:37], v[20:21], 0, s[20:21]
	v_lshl_add_u64 v[38:39], v[18:19], 0, s[20:21]
	v_lshl_add_u64 v[40:41], v[16:17], 0, s[20:21]
	v_lshl_add_u64 v[42:43], v[14:15], 0, s[20:21]
	v_lshl_add_u64 v[44:45], v[12:13], 0, s[20:21]
	v_lshl_add_u64 v[46:47], v[10:11], 0, s[20:21]
	v_lshl_add_u64 v[48:49], v[8:9], 0, s[20:21]
	v_lshl_add_u64 v[50:51], v[6:7], 0, s[20:21]
	global_load_dword v52, v[36:37], off nt
	global_load_dword v53, v[38:39], off nt
	global_load_dword v54, v[40:41], off nt
	global_load_dword v55, v[42:43], off nt
	global_load_dword v56, v[44:45], off nt
	global_load_dword v57, v[46:47], off nt
	global_load_dword v58, v[48:49], off nt
	global_load_dword v59, v[50:51], off nt
	s_add_u32 s20, s20, 0x58000
	s_addc_u32 s21, s21, 0
	v_lshl_add_u64 v[36:37], v[20:21], 0, s[20:21]
	v_lshl_add_u64 v[38:39], v[18:19], 0, s[20:21]
	v_lshl_add_u64 v[40:41], v[16:17], 0, s[20:21]
	v_lshl_add_u64 v[42:43], v[14:15], 0, s[20:21]
	v_lshl_add_u64 v[44:45], v[12:13], 0, s[20:21]
	v_lshl_add_u64 v[46:47], v[10:11], 0, s[20:21]
	v_lshl_add_u64 v[48:49], v[8:9], 0, s[20:21]
	v_lshl_add_u64 v[50:51], v[6:7], 0, s[20:21]
	global_load_dword v60, v[36:37], off nt
	global_load_dword v61, v[38:39], off nt
	global_load_dword v62, v[40:41], off nt
	global_load_dword v63, v[42:43], off nt
	global_load_dword v64, v[44:45], off nt
	global_load_dword v65, v[46:47], off nt
	global_load_dword v66, v[48:49], off nt
	global_load_dword v67, v[50:51], off nt
	s_add_u32 s20, s20, 0x58000
	s_addc_u32 s21, s21, 0
	v_lshl_add_u64 v[36:37], v[20:21], 0, s[20:21]
	v_lshl_add_u64 v[38:39], v[18:19], 0, s[20:21]
	v_lshl_add_u64 v[40:41], v[16:17], 0, s[20:21]
	v_lshl_add_u64 v[42:43], v[14:15], 0, s[20:21]
	v_lshl_add_u64 v[44:45], v[12:13], 0, s[20:21]
	v_lshl_add_u64 v[46:47], v[10:11], 0, s[20:21]
	v_lshl_add_u64 v[48:49], v[8:9], 0, s[20:21]
	v_lshl_add_u64 v[50:51], v[6:7], 0, s[20:21]
	global_load_dword v68, v[36:37], off nt
	global_load_dword v69, v[38:39], off nt
	global_load_dword v70, v[40:41], off nt
	global_load_dword v71, v[42:43], off nt
	global_load_dword v72, v[44:45], off nt
	global_load_dword v73, v[46:47], off nt
	global_load_dword v74, v[48:49], off nt
	global_load_dword v75, v[50:51], off nt
	s_add_u32 s20, s20, 0x58000
	s_addc_u32 s21, s21, 0
	v_lshl_add_u64 v[36:37], v[20:21], 0, s[20:21]
	v_lshl_add_u64 v[38:39], v[18:19], 0, s[20:21]
	v_lshl_add_u64 v[40:41], v[16:17], 0, s[20:21]
	v_lshl_add_u64 v[42:43], v[14:15], 0, s[20:21]
	v_lshl_add_u64 v[44:45], v[12:13], 0, s[20:21]
	v_lshl_add_u64 v[46:47], v[10:11], 0, s[20:21]
	v_lshl_add_u64 v[48:49], v[8:9], 0, s[20:21]
	v_lshl_add_u64 v[50:51], v[6:7], 0, s[20:21]
	global_load_dword v76, v[36:37], off nt
	global_load_dword v77, v[38:39], off nt
	global_load_dword v78, v[40:41], off nt
	global_load_dword v79, v[42:43], off nt
	global_load_dword v80, v[44:45], off nt
	global_load_dword v81, v[46:47], off nt
	global_load_dword v82, v[48:49], off nt
	global_load_dword v83, v[50:51], off nt
	s_add_u32 s20, s20, 0x58000
	s_addc_u32 s21, s21, 0
	v_add_u32_e32 v36, 0x400, v35
	s_waitcnt vmcnt(30)
	ds_write2_b32 v35, v52, v53 offset1:66
	s_waitcnt vmcnt(28)
	ds_write2_b32 v35, v54, v55 offset0:132 offset1:198
	s_waitcnt vmcnt(26)
	ds_write2_b32 v36, v56, v57 offset0:8 offset1:74
	s_waitcnt vmcnt(24)
	ds_write2_b32 v36, v58, v59 offset0:140 offset1:206
	v_add_u32_e32 v35, 0x840, v35
	v_add_u32_e32 v36, 0x400, v35
	s_waitcnt vmcnt(22)
	ds_write2_b32 v35, v60, v61 offset1:66
	s_waitcnt vmcnt(20)
	ds_write2_b32 v35, v62, v63 offset0:132 offset1:198
	s_waitcnt vmcnt(18)
	ds_write2_b32 v36, v64, v65 offset0:8 offset1:74
	s_waitcnt vmcnt(16)
	ds_write2_b32 v36, v66, v67 offset0:140 offset1:206
	v_add_u32_e32 v35, 0x840, v35
	v_add_u32_e32 v36, 0x400, v35
	s_waitcnt vmcnt(14)
	ds_write2_b32 v35, v68, v69 offset1:66
	s_waitcnt vmcnt(12)
	ds_write2_b32 v35, v70, v71 offset0:132 offset1:198
	s_waitcnt vmcnt(10)
	ds_write2_b32 v36, v72, v73 offset0:8 offset1:74
	s_waitcnt vmcnt(8)
	ds_write2_b32 v36, v74, v75 offset0:140 offset1:206
	v_add_u32_e32 v35, 0x840, v35
	v_add_u32_e32 v36, 0x400, v35
	s_waitcnt vmcnt(6)
	ds_write2_b32 v35, v76, v77 offset1:66
	s_waitcnt vmcnt(4)
	ds_write2_b32 v35, v78, v79 offset0:132 offset1:198
	s_waitcnt vmcnt(2)
	ds_write2_b32 v36, v80, v81 offset0:8 offset1:74
	s_waitcnt vmcnt(0)
	ds_write2_b32 v36, v82, v83 offset0:140 offset1:206
	v_add_u32_e32 v35, 0x840, v35
	s_waitcnt lgkmcnt(0)
	ds_read2_b32 v[10:11], v23 offset1:8
	ds_read2_b32 v[14:15], v23 offset0:33 offset1:41
	ds_read2_b32 v[16:17], v23 offset0:66 offset1:74
	ds_read2_b32 v[18:19], v23 offset0:99 offset1:107
	ds_read2_b32 v[20:21], v23 offset0:132 offset1:140
	s_waitcnt lgkmcnt(4)
	v_bfe_u32 v6, v10, 16, 1
	v_add3_u32 v6, v10, v6, s26
	s_waitcnt lgkmcnt(3)
	v_bfe_u32 v7, v14, 16, 1
	v_lshrrev_b32_e32 v6, 16, v6
	v_add3_u32 v7, v14, v7, s26
	ds_read2_b32 v[36:37], v23 offset0:165 offset1:173
	v_and_or_b32 v6, v7, s27, v6
	s_waitcnt lgkmcnt(3)
	v_bfe_u32 v7, v16, 16, 1
	v_add3_u32 v7, v16, v7, s26
	s_waitcnt lgkmcnt(2)
	v_bfe_u32 v8, v18, 16, 1
	ds_read2_b32 v[38:39], v23 offset0:198 offset1:206
	v_lshrrev_b32_e32 v7, 16, v7
	v_add3_u32 v8, v18, v8, s26
	ds_read2_b32 v[40:41], v23 offset0:231 offset1:239
	v_and_or_b32 v7, v8, s27, v7
	s_waitcnt lgkmcnt(3)
	v_bfe_u32 v8, v20, 16, 1
	s_lshl_b32 s20, s23, 5
	s_lshl_b32 s21, s23, 6
	v_add3_u32 v8, v20, v8, s26
	s_waitcnt lgkmcnt(2)
	v_bfe_u32 v9, v36, 16, 1
	s_and_b32 s21, s21, 0x3f00
	s_and_b32 s20, s20, 0x60
	v_lshrrev_b32_e32 v8, 16, v8
	v_add3_u32 v9, v36, v9, s26
	s_or_b32 s20, s21, s20
	s_and_b32 s19, 0xffff, s19
	v_and_or_b32 v8, v9, s27, v8
	s_waitcnt lgkmcnt(1)
	v_bfe_u32 v9, v38, 16, 1
	s_or_b32 s23, s20, 0x80
	s_lshl_b32 s19, s19, 1
	v_add3_u32 v9, v38, v9, s26
	s_waitcnt lgkmcnt(0)
	v_bfe_u32 v10, v40, 16, 1
	s_add_u32 s20, s30, s19
	v_lshrrev_b32_e32 v9, 16, v9
	v_add3_u32 v10, v40, v10, s26
	s_addc_u32 s21, s31, 0
	v_and_or_b32 v9, v10, s27, v9
	v_or_b32_e32 v10, s23, v22
	v_lshl_add_u64 v[12:13], s[20:21], 0, v[2:3]
	v_lshlrev_b32_e32 v42, 12, v10
	v_mov_b32_e32 v43, v3
	v_lshl_add_u64 v[42:43], v[12:13], 0, v[42:43]
	global_store_dwordx4 v[42:43], v[6:9], off nt
	v_bfe_u32 v10, v41, 16, 1
	v_add3_u32 v10, v41, v10, s26
	v_bfe_u32 v6, v11, 16, 1
	v_add3_u32 v6, v11, v6, s26
	v_bfe_u32 v7, v15, 16, 1
	v_lshrrev_b32_e32 v6, 16, v6
	v_add3_u32 v7, v15, v7, s26
	v_and_or_b32 v6, v7, s27, v6
	v_bfe_u32 v7, v17, 16, 1
	v_add3_u32 v7, v17, v7, s26
	v_bfe_u32 v8, v19, 16, 1
	v_lshrrev_b32_e32 v7, 16, v7
	v_add3_u32 v8, v19, v8, s26
	v_and_or_b32 v7, v8, s27, v7
	v_bfe_u32 v8, v21, 16, 1
	v_add3_u32 v8, v21, v8, s26
	v_bfe_u32 v9, v37, 16, 1
	v_lshrrev_b32_e32 v8, 16, v8
	v_add3_u32 v9, v37, v9, s26
	v_and_or_b32 v8, v9, s27, v8
	v_bfe_u32 v9, v39, 16, 1
	v_add3_u32 v9, v39, v9, s26
	v_lshrrev_b32_e32 v9, 16, v9
	v_and_or_b32 v9, v10, s27, v9
	v_or_b32_e32 v10, s23, v24
	v_lshlrev_b32_e32 v10, 12, v10
	v_mov_b32_e32 v11, v3
	ds_read2_b32 v[14:15], v23 offset0:16 offset1:24
	v_lshl_add_u64 v[10:11], v[12:13], 0, v[10:11]
	global_store_dwordx4 v[10:11], v[6:9], off nt
	ds_read2_b32 v[10:11], v23 offset0:49 offset1:57
	ds_read2_b32 v[16:17], v23 offset0:82 offset1:90
	ds_read2_b32 v[18:19], v23 offset0:115 offset1:123
	s_waitcnt lgkmcnt(3)
	v_bfe_u32 v6, v14, 16, 1
	v_add3_u32 v6, v14, v6, s26
	s_waitcnt lgkmcnt(2)
	v_bfe_u32 v7, v10, 16, 1
	ds_read2_b32 v[20:21], v23 offset0:148 offset1:156
	v_lshrrev_b32_e32 v6, 16, v6
	v_add3_u32 v7, v10, v7, s26
	ds_read2_b32 v[36:37], v23 offset0:181 offset1:189
	v_and_or_b32 v6, v7, s27, v6
	s_waitcnt lgkmcnt(3)
	v_bfe_u32 v7, v16, 16, 1
	v_add3_u32 v7, v16, v7, s26
	s_waitcnt lgkmcnt(2)
	v_bfe_u32 v8, v18, 16, 1
	ds_read2_b32 v[38:39], v23 offset0:214 offset1:222
	v_lshrrev_b32_e32 v7, 16, v7
	v_add3_u32 v8, v18, v8, s26
	ds_read2_b32 v[40:41], v23 offset0:247 offset1:255
	v_and_or_b32 v7, v8, s27, v7
	s_waitcnt lgkmcnt(3)
	v_bfe_u32 v8, v20, 16, 1
	v_add3_u32 v8, v20, v8, s26
	s_waitcnt lgkmcnt(2)
	v_bfe_u32 v9, v36, 16, 1
	v_lshrrev_b32_e32 v8, 16, v8
	v_add3_u32 v9, v36, v9, s26
	v_and_or_b32 v8, v9, s27, v8
	s_waitcnt lgkmcnt(1)
	v_bfe_u32 v9, v38, 16, 1
	v_add3_u32 v9, v38, v9, s26
	s_waitcnt lgkmcnt(0)
	v_bfe_u32 v10, v40, 16, 1
	v_lshrrev_b32_e32 v9, 16, v9
	v_add3_u32 v10, v40, v10, s26
	v_and_or_b32 v9, v10, s27, v9
	v_or_b32_e32 v10, s23, v25
	v_lshlrev_b32_e32 v42, 12, v10
	v_mov_b32_e32 v43, v3
	v_lshl_add_u64 v[42:43], v[12:13], 0, v[42:43]
	global_store_dwordx4 v[42:43], v[6:9], off nt
	v_bfe_u32 v10, v41, 16, 1
	v_add3_u32 v10, v41, v10, s26
	v_bfe_u32 v6, v15, 16, 1
	v_add3_u32 v6, v15, v6, s26
	v_bfe_u32 v7, v11, 16, 1
	v_lshrrev_b32_e32 v6, 16, v6
	v_add3_u32 v7, v11, v7, s26
	v_and_or_b32 v6, v7, s27, v6
	v_bfe_u32 v7, v17, 16, 1
	v_add3_u32 v7, v17, v7, s26
	v_bfe_u32 v8, v19, 16, 1
	v_lshrrev_b32_e32 v7, 16, v7
	v_add3_u32 v8, v19, v8, s26
	v_and_or_b32 v7, v8, s27, v7
	v_bfe_u32 v8, v21, 16, 1
	v_add3_u32 v8, v21, v8, s26
	v_bfe_u32 v9, v37, 16, 1
	v_lshrrev_b32_e32 v8, 16, v8
	v_add3_u32 v9, v37, v9, s26
	v_and_or_b32 v8, v9, s27, v8
	v_bfe_u32 v9, v39, 16, 1
	v_add3_u32 v9, v39, v9, s26
	v_lshrrev_b32_e32 v9, 16, v9
	v_and_or_b32 v9, v10, s27, v9
	v_or_b32_e32 v10, s23, v26
	v_lshlrev_b32_e32 v10, 12, v10
	v_mov_b32_e32 v11, v3
	v_lshl_add_u64 v[10:11], v[12:13], 0, v[10:11]
	global_store_dwordx4 v[10:11], v[6:9], off nt
	s_waitcnt lgkmcnt(0)

.LBB0_59:
	v_lshl_add_u64 v[36:37], v[20:21], 0, s[22:23]
	v_lshl_add_u64 v[38:39], v[18:19], 0, s[22:23]
	v_lshl_add_u64 v[40:41], v[16:17], 0, s[22:23]
	v_lshl_add_u64 v[42:43], v[14:15], 0, s[22:23]
	v_lshl_add_u64 v[44:45], v[12:13], 0, s[22:23]
	v_lshl_add_u64 v[46:47], v[10:11], 0, s[22:23]
	v_lshl_add_u64 v[48:49], v[8:9], 0, s[22:23]
	v_lshl_add_u64 v[50:51], v[6:7], 0, s[22:23]
	global_load_dword v52, v[36:37], off nt
	global_load_dword v53, v[38:39], off nt
	global_load_dword v54, v[40:41], off nt
	global_load_dword v55, v[42:43], off nt
	global_load_dword v56, v[44:45], off nt
	global_load_dword v57, v[46:47], off nt
	global_load_dword v58, v[48:49], off nt
	global_load_dword v59, v[50:51], off nt
	s_add_u32 s22, s22, 0x58000
	s_addc_u32 s23, s23, 0
	v_lshl_add_u64 v[36:37], v[20:21], 0, s[22:23]
	v_lshl_add_u64 v[38:39], v[18:19], 0, s[22:23]
	v_lshl_add_u64 v[40:41], v[16:17], 0, s[22:23]
	v_lshl_add_u64 v[42:43], v[14:15], 0, s[22:23]
	v_lshl_add_u64 v[44:45], v[12:13], 0, s[22:23]
	v_lshl_add_u64 v[46:47], v[10:11], 0, s[22:23]
	v_lshl_add_u64 v[48:49], v[8:9], 0, s[22:23]
	v_lshl_add_u64 v[50:51], v[6:7], 0, s[22:23]
	global_load_dword v60, v[36:37], off nt
	global_load_dword v61, v[38:39], off nt
	global_load_dword v62, v[40:41], off nt
	global_load_dword v63, v[42:43], off nt
	global_load_dword v64, v[44:45], off nt
	global_load_dword v65, v[46:47], off nt
	global_load_dword v66, v[48:49], off nt
	global_load_dword v67, v[50:51], off nt
	s_add_u32 s22, s22, 0x58000
	s_addc_u32 s23, s23, 0
	v_lshl_add_u64 v[36:37], v[20:21], 0, s[22:23]
	v_lshl_add_u64 v[38:39], v[18:19], 0, s[22:23]
	v_lshl_add_u64 v[40:41], v[16:17], 0, s[22:23]
	v_lshl_add_u64 v[42:43], v[14:15], 0, s[22:23]
	v_lshl_add_u64 v[44:45], v[12:13], 0, s[22:23]
	v_lshl_add_u64 v[46:47], v[10:11], 0, s[22:23]
	v_lshl_add_u64 v[48:49], v[8:9], 0, s[22:23]
	v_lshl_add_u64 v[50:51], v[6:7], 0, s[22:23]
	global_load_dword v68, v[36:37], off nt
	global_load_dword v69, v[38:39], off nt
	global_load_dword v70, v[40:41], off nt
	global_load_dword v71, v[42:43], off nt
	global_load_dword v72, v[44:45], off nt
	global_load_dword v73, v[46:47], off nt
	global_load_dword v74, v[48:49], off nt
	global_load_dword v75, v[50:51], off nt
	s_add_u32 s22, s22, 0x58000
	s_addc_u32 s23, s23, 0
	v_lshl_add_u64 v[36:37], v[20:21], 0, s[22:23]
	v_lshl_add_u64 v[38:39], v[18:19], 0, s[22:23]
	v_lshl_add_u64 v[40:41], v[16:17], 0, s[22:23]
	v_lshl_add_u64 v[42:43], v[14:15], 0, s[22:23]
	v_lshl_add_u64 v[44:45], v[12:13], 0, s[22:23]
	v_lshl_add_u64 v[46:47], v[10:11], 0, s[22:23]
	v_lshl_add_u64 v[48:49], v[8:9], 0, s[22:23]
	v_lshl_add_u64 v[50:51], v[6:7], 0, s[22:23]
	global_load_dword v76, v[36:37], off nt
	global_load_dword v77, v[38:39], off nt
	global_load_dword v78, v[40:41], off nt
	global_load_dword v79, v[42:43], off nt
	global_load_dword v80, v[44:45], off nt
	global_load_dword v81, v[46:47], off nt
	global_load_dword v82, v[48:49], off nt
	global_load_dword v83, v[50:51], off nt
	s_add_u32 s22, s22, 0x58000
	s_addc_u32 s23, s23, 0
	v_add_u32_e32 v36, 0x400, v35
	s_waitcnt vmcnt(30)
	ds_write2_b32 v35, v52, v53 offset1:66
	s_waitcnt vmcnt(28)
	ds_write2_b32 v35, v54, v55 offset0:132 offset1:198
	s_waitcnt vmcnt(26)
	ds_write2_b32 v36, v56, v57 offset0:8 offset1:74
	s_waitcnt vmcnt(24)
	ds_write2_b32 v36, v58, v59 offset0:140 offset1:206
	v_add_u32_e32 v35, 0x840, v35
	v_add_u32_e32 v36, 0x400, v35
	s_waitcnt vmcnt(22)
	ds_write2_b32 v35, v60, v61 offset1:66
	s_waitcnt vmcnt(20)
	ds_write2_b32 v35, v62, v63 offset0:132 offset1:198
	s_waitcnt vmcnt(18)
	ds_write2_b32 v36, v64, v65 offset0:8 offset1:74
	s_waitcnt vmcnt(16)
	ds_write2_b32 v36, v66, v67 offset0:140 offset1:206
	v_add_u32_e32 v35, 0x840, v35
	v_add_u32_e32 v36, 0x400, v35
	s_waitcnt vmcnt(14)
	ds_write2_b32 v35, v68, v69 offset1:66
	s_waitcnt vmcnt(12)
	ds_write2_b32 v35, v70, v71 offset0:132 offset1:198
	s_waitcnt vmcnt(10)
	ds_write2_b32 v36, v72, v73 offset0:8 offset1:74
	s_waitcnt vmcnt(8)
	ds_write2_b32 v36, v74, v75 offset0:140 offset1:206
	v_add_u32_e32 v35, 0x840, v35
	v_add_u32_e32 v36, 0x400, v35
	s_waitcnt vmcnt(6)
	ds_write2_b32 v35, v76, v77 offset1:66
	s_waitcnt vmcnt(4)
	ds_write2_b32 v35, v78, v79 offset0:132 offset1:198
	s_waitcnt vmcnt(2)
	ds_write2_b32 v36, v80, v81 offset0:8 offset1:74
	s_waitcnt vmcnt(0)
	ds_write2_b32 v36, v82, v83 offset0:140 offset1:206
	v_add_u32_e32 v35, 0x840, v35
	s_waitcnt lgkmcnt(0)
	ds_read2_b32 v[10:11], v23 offset1:8
	ds_read2_b32 v[14:15], v23 offset0:33 offset1:41
	ds_read2_b32 v[16:17], v23 offset0:66 offset1:74
	ds_read2_b32 v[18:19], v23 offset0:99 offset1:107
	ds_read2_b32 v[20:21], v23 offset0:132 offset1:140
	s_waitcnt lgkmcnt(4)
	v_bfe_u32 v6, v10, 16, 1
	v_add3_u32 v6, v10, v6, s26
	s_waitcnt lgkmcnt(3)
	v_bfe_u32 v7, v14, 16, 1
	v_lshrrev_b32_e32 v6, 16, v6
	v_add3_u32 v7, v14, v7, s26
	ds_read2_b32 v[36:37], v23 offset0:165 offset1:173
	v_and_or_b32 v6, v7, s27, v6
	s_waitcnt lgkmcnt(3)
	v_bfe_u32 v7, v16, 16, 1
	v_add3_u32 v7, v16, v7, s26
	s_waitcnt lgkmcnt(2)
	v_bfe_u32 v8, v18, 16, 1
	ds_read2_b32 v[38:39], v23 offset0:198 offset1:206
	s_lshl_b32 s19, s19, 6
	v_lshrrev_b32_e32 v7, 16, v7
	v_add3_u32 v8, v18, v8, s26
	ds_read2_b32 v[40:41], v23 offset0:231 offset1:239
	s_and_b32 s19, s19, 0xffffff00
	s_and_b32 s20, s20, 0x60
	v_and_or_b32 v7, v8, s27, v7
	s_waitcnt lgkmcnt(3)
	v_bfe_u32 v8, v20, 16, 1
	s_or_b32 s20, s20, s19
	s_ashr_i32 s19, s18, 31
	v_add3_u32 v8, v20, v8, s26
	s_waitcnt lgkmcnt(2)
	v_bfe_u32 v9, v36, 16, 1
	s_lshl_b64 s[18:19], s[18:19], 1
	v_lshrrev_b32_e32 v8, 16, v8
	v_add3_u32 v9, v36, v9, s26
	s_add_u32 s18, s30, s18
	v_and_or_b32 v8, v9, s27, v8
	s_waitcnt lgkmcnt(1)
	v_bfe_u32 v9, v38, 16, 1
	v_or_b32_e32 v42, s20, v22
	s_addc_u32 s19, s31, s19
	v_add3_u32 v9, v38, v9, s26
	s_waitcnt lgkmcnt(0)
	v_bfe_u32 v10, v40, 16, 1
	v_ashrrev_i32_e32 v43, 31, v42
	v_lshl_add_u64 v[12:13], s[18:19], 0, v[2:3]
	v_lshrrev_b32_e32 v9, 16, v9
	v_add3_u32 v10, v40, v10, s26
	v_lshlrev_b64 v[42:43], 12, v[42:43]
	v_and_or_b32 v9, v10, s27, v9
	v_lshl_add_u64 v[42:43], v[12:13], 0, v[42:43]
	global_store_dwordx4 v[42:43], v[6:9], off nt
	v_bfe_u32 v10, v41, 16, 1
	v_add3_u32 v10, v41, v10, s26
	v_bfe_u32 v6, v11, 16, 1
	v_add3_u32 v6, v11, v6, s26
	v_bfe_u32 v7, v15, 16, 1
	v_lshrrev_b32_e32 v6, 16, v6
	v_add3_u32 v7, v15, v7, s26
	v_and_or_b32 v6, v7, s27, v6
	v_bfe_u32 v7, v17, 16, 1
	v_add3_u32 v7, v17, v7, s26
	v_bfe_u32 v8, v19, 16, 1
	v_lshrrev_b32_e32 v7, 16, v7
	v_add3_u32 v8, v19, v8, s26
	v_and_or_b32 v7, v8, s27, v7
	v_bfe_u32 v8, v21, 16, 1
	v_add3_u32 v8, v21, v8, s26
	v_bfe_u32 v9, v37, 16, 1
	v_lshrrev_b32_e32 v8, 16, v8
	v_add3_u32 v9, v37, v9, s26
	v_and_or_b32 v8, v9, s27, v8
	v_bfe_u32 v9, v39, 16, 1
	v_add3_u32 v9, v39, v9, s26
	v_lshrrev_b32_e32 v9, 16, v9
	v_and_or_b32 v9, v10, s27, v9
	v_or_b32_e32 v10, s20, v24
	v_ashrrev_i32_e32 v11, 31, v10
	v_lshlrev_b64 v[10:11], 12, v[10:11]
	ds_read2_b32 v[14:15], v23 offset0:16 offset1:24
	v_lshl_add_u64 v[10:11], v[12:13], 0, v[10:11]
	global_store_dwordx4 v[10:11], v[6:9], off nt
	ds_read2_b32 v[10:11], v23 offset0:49 offset1:57
	ds_read2_b32 v[16:17], v23 offset0:82 offset1:90
	ds_read2_b32 v[18:19], v23 offset0:115 offset1:123
	s_waitcnt lgkmcnt(3)
	v_bfe_u32 v6, v14, 16, 1
	v_add3_u32 v6, v14, v6, s26
	s_waitcnt lgkmcnt(2)
	v_bfe_u32 v7, v10, 16, 1
	ds_read2_b32 v[20:21], v23 offset0:148 offset1:156
	v_lshrrev_b32_e32 v6, 16, v6
	v_add3_u32 v7, v10, v7, s26
	ds_read2_b32 v[36:37], v23 offset0:181 offset1:189
	v_and_or_b32 v6, v7, s27, v6
	s_waitcnt lgkmcnt(3)
	v_bfe_u32 v7, v16, 16, 1
	v_add3_u32 v7, v16, v7, s26
	s_waitcnt lgkmcnt(2)
	v_bfe_u32 v8, v18, 16, 1
	ds_read2_b32 v[38:39], v23 offset0:214 offset1:222
	v_lshrrev_b32_e32 v7, 16, v7
	v_add3_u32 v8, v18, v8, s26
	ds_read2_b32 v[40:41], v23 offset0:247 offset1:255
	v_and_or_b32 v7, v8, s27, v7
	s_waitcnt lgkmcnt(3)
	v_bfe_u32 v8, v20, 16, 1
	v_add3_u32 v8, v20, v8, s26
	s_waitcnt lgkmcnt(2)
	v_bfe_u32 v9, v36, 16, 1
	v_lshrrev_b32_e32 v8, 16, v8
	v_add3_u32 v9, v36, v9, s26
	v_and_or_b32 v8, v9, s27, v8
	s_waitcnt lgkmcnt(1)
	v_bfe_u32 v9, v38, 16, 1
	v_or_b32_e32 v42, s20, v25
	v_add3_u32 v9, v38, v9, s26
	s_waitcnt lgkmcnt(0)
	v_bfe_u32 v10, v40, 16, 1
	v_ashrrev_i32_e32 v43, 31, v42
	v_lshrrev_b32_e32 v9, 16, v9
	v_add3_u32 v10, v40, v10, s26
	v_lshlrev_b64 v[42:43], 12, v[42:43]
	v_and_or_b32 v9, v10, s27, v9
	v_lshl_add_u64 v[42:43], v[12:13], 0, v[42:43]
	global_store_dwordx4 v[42:43], v[6:9], off nt
	v_bfe_u32 v10, v41, 16, 1
	v_add3_u32 v10, v41, v10, s26
	v_bfe_u32 v6, v15, 16, 1
	v_add3_u32 v6, v15, v6, s26
	v_bfe_u32 v7, v11, 16, 1
	v_lshrrev_b32_e32 v6, 16, v6
	v_add3_u32 v7, v11, v7, s26
	v_and_or_b32 v6, v7, s27, v6
	v_bfe_u32 v7, v17, 16, 1
	v_add3_u32 v7, v17, v7, s26
	v_bfe_u32 v8, v19, 16, 1
	v_lshrrev_b32_e32 v7, 16, v7
	v_add3_u32 v8, v19, v8, s26
	v_and_or_b32 v7, v8, s27, v7
	v_bfe_u32 v8, v21, 16, 1
	v_add3_u32 v8, v21, v8, s26
	v_bfe_u32 v9, v37, 16, 1
	v_lshrrev_b32_e32 v8, 16, v8
	v_add3_u32 v9, v37, v9, s26
	v_and_or_b32 v8, v9, s27, v8
	v_bfe_u32 v9, v39, 16, 1
	v_add3_u32 v9, v39, v9, s26
	v_lshrrev_b32_e32 v9, 16, v9
	v_and_or_b32 v9, v10, s27, v9
	v_or_b32_e32 v10, s20, v26
	v_ashrrev_i32_e32 v11, 31, v10
	v_lshlrev_b64 v[10:11], 12, v[10:11]
	v_lshl_add_u64 v[10:11], v[12:13], 0, v[10:11]
	global_store_dwordx4 v[10:11], v[6:9], off nt
	s_waitcnt lgkmcnt(0)
	s_branch .LBB0_10
